# ret_out cross-chunk loop: 8 R-fragment loads per direction issued together with counted waits per MFMA
# baseline (speedup 1.0000x reference)
; #define LAUNDER_V(x) asm volatile("" : "+v"(x))
; __device__ __forceinline__ unsigned pk2(float lo, float hi) { return pg8::pk_bf16_rne(lo, hi); }
; __device__ __forceinline__ float bf2f(unsigned short u) { return __uint_as_float(((unsigned)u) << 16); }
; __device__ __forceinline__ float half_sum(float v) { v = row16_allsum(v); v = rows_pair_sum(v); return v; }
; __device__ __forceinline__ int crow(int r, int hi) { return (r & 3) + 8 * (r >> 2) + 4 * hi; }
; #define MFMA32(a, b, c) __builtin_amdgcn_mfma_f32_32x32x16_bf16((a), (b), (c), 0, 0, 0)
; __device__ __forceinline__ void ret_out(const Params& P, int l, unsigned char* lds, int u, int tid) {
;     ...
;     for (int dir = 0; dir < 2; ++dir) {
;         const bf16_t* Rt = RT + ((size_t)unit * 2 + dir) * 4096;
;         const float wq = dir == 0 ? __builtin_amdgcn_exp2f(lgf2 * (float)(cq + 1)) : __builtin_amdgcn_exp2f(lgb2 * (float)(128 - cq));
; #pragma unroll
;         for (int s = 0; s < 4; ++s) {
;             u32x4 w;
; #pragma unroll
;             for (int j = 0; j < 4; ++j) w[j] = pk2(bf2f((unsigned short)qr[s][2 * j]) * wq, bf2f((unsigned short)qr[s][2 * j + 1]) * wq);
;             const bf16x8 A = __builtin_bit_cast(bf16x8, w);
;             const bf16x8 b0 = *(const bf16x8*)(Rt + r32 * 64 + 16 * s + 8 * hi), b1 = *(const bf16x8*)(Rt + (32 + r32) * 64 + 16 * s + 8 * hi);
;             o0 = MFMA32(A, b0, o0); o1 = MFMA32(A, b1, o1);
;         }
;     }
;     const float g0 = gn[h * 64 + r32], g1 = gn[h * 64 + 32 + r32];
;     int c0f = c0; LAUNDER_V(c0f);
; #pragma unroll
;     for (int r = 0; r < 16; ++r) {
;         const float mean = half_sum(o0[r] + o1[r]) * (1.0f / 64.0f);
;         const float d0 = o0[r] - mean, d1 = o1[r] - mean;
;         const float var = half_sum(d0 * d0 + d1 * d1) * (1.0f / 64.0f);
;         const float rstd = 1.0f / sqrtf(var + 1e-5f);
;         const size_t t = tc + c0f + crow(r, hi);
;         const float ga = bf2f(ZR[t * 1024 + 768 + h * 64 + r32]), gb = bf2f(ZR[t * 1024 + 768 + h * 64 + 32 + r32]);
;         const float sa = ga / (1.0f + __expf(-ga)), sb = gb / (1.0f + __expf(-gb));
;         MIX[t * 1024 + 768 + h * 64 + r32] = (bf16_t)(pk2(sa * d0 * rstd * g0, 0.f) & 0xffffu);
;         MIX[t * 1024 + 768 + h * 64 + 32 + r32] = (bf16_t)(pk2(sb * d1 * rstd * g1, 0.f) & 0xffffu);
.LBB0_145:
	v_lshl_add_u64 v[50:51], s[28:29], 1, v[32:33]
	v_cndmask_b32_e64 v64, v67, v74, s[92:93]
	v_lshl_add_u64 v[88:89], v[50:51], 0, v[152:153]
	v_pk_mul_f32 v[76:77], v[64:65], v[34:35] op_sel_hi:[0,1]
	v_pk_mul_f32 v[78:79], v[64:65], v[36:37] op_sel_hi:[0,1]
	v_add_co_u32_e32 v84, vcc, s36, v88
	v_cvt_pk_bf16_f32 v76, v76, v77
	v_cvt_pk_bf16_f32 v77, v78, v79
	v_pk_mul_f32 v[78:79], v[64:65], v[38:39] op_sel_hi:[0,1]
	v_pk_mul_f32 v[80:81], v[64:65], v[40:41] op_sel_hi:[0,1]
	v_addc_co_u32_e32 v85, vcc, 0, v89, vcc
	v_cvt_pk_bf16_f32 v78, v78, v79
	v_cvt_pk_bf16_f32 v79, v80, v81
	global_load_dwordx4 v[80:83], v[88:89], off
	s_mov_b64 s[28:29], 0x1000
	global_load_dwordx4 v[84:87], v[84:85], off
	v_lshl_add_u64 v[50:51], v[88:89], 0, s[28:29]
	global_load_dwordx4 v[90:93], v[88:89], off offset:32
	global_load_dwordx4 v[94:97], v[50:51], off offset:32
	global_load_dwordx4 v[98:101], v[88:89], off offset:64
	global_load_dwordx4 v[102:105], v[50:51], off offset:64
	global_load_dwordx4 v[106:109], v[88:89], off offset:96
	global_load_dwordx4 v[110:113], v[50:51], off offset:96
	s_and_b64 vcc, exec, s[92:93]
	s_mov_b64 s[92:93], 0
	s_waitcnt vmcnt(7)
	v_mfma_f32_32x32x16_bf16 v[0:15], v[76:79], v[80:83], v[0:15]
	v_mul_f32_e64 v80, v64, v56
	v_mul_f32_e64 v81, v64, v57
	s_waitcnt vmcnt(6)
	v_mfma_f32_32x32x16_bf16 v[16:31], v[76:79], v[84:87], v[16:31]
	v_mul_f32_e64 v76, v64, v42
	v_mul_f32_e64 v77, v64, v43
	v_mul_f32_e64 v78, v64, v44
	v_mul_f32_e64 v79, v64, v45
	v_cvt_pk_bf16_f32 v76, v76, v77
	v_cvt_pk_bf16_f32 v77, v78, v79
	v_pk_mul_f32 v[78:79], v[64:65], v[46:47] op_sel_hi:[0,1]
	v_cvt_pk_bf16_f32 v78, v78, v79
	v_cvt_pk_bf16_f32 v79, v80, v81
	s_nop 0
	s_nop 0
	s_waitcnt vmcnt(5)
	v_mfma_f32_32x32x16_bf16 v[0:15], v[76:79], v[90:93], v[0:15]
	v_mul_f32_e64 v80, v64, v62
	v_mul_f32_e64 v81, v64, v63
	s_waitcnt vmcnt(4)
	v_mfma_f32_32x32x16_bf16 v[16:31], v[76:79], v[94:97], v[16:31]
	v_mul_f32_e64 v76, v64, v58
	v_mul_f32_e64 v77, v64, v59
	v_mul_f32_e64 v78, v64, v60
	v_mul_f32_e64 v79, v64, v61
	v_cvt_pk_bf16_f32 v76, v76, v77
	v_cvt_pk_bf16_f32 v77, v78, v79
	v_pk_mul_f32 v[78:79], v[64:65], v[52:53] op_sel_hi:[0,1]
	v_cvt_pk_bf16_f32 v78, v78, v79
	v_cvt_pk_bf16_f32 v79, v80, v81
	s_nop 0
	s_nop 0
	s_waitcnt vmcnt(3)
	v_mfma_f32_32x32x16_bf16 v[0:15], v[76:79], v[98:101], v[0:15]
	v_mul_f32_e64 v80, v64, v72
	v_mul_f32_e64 v81, v64, v73
	s_waitcnt vmcnt(2)
	v_mfma_f32_32x32x16_bf16 v[16:31], v[76:79], v[102:105], v[16:31]
	v_mul_f32_e64 v76, v64, v54
	v_mul_f32_e64 v77, v64, v55
	v_mul_f32_e64 v78, v64, v70
	v_mul_f32_e64 v79, v64, v71
	v_cvt_pk_bf16_f32 v76, v76, v77
	v_cvt_pk_bf16_f32 v77, v78, v79
	v_pk_mul_f32 v[78:79], v[64:65], v[48:49] op_sel_hi:[0,1]
	v_cvt_pk_bf16_f32 v78, v78, v79
	v_cvt_pk_bf16_f32 v79, v80, v81
	s_nop 0
	s_nop 0
	s_waitcnt vmcnt(1)
	v_mfma_f32_32x32x16_bf16 v[0:15], v[76:79], v[106:109], v[0:15]
	s_waitcnt vmcnt(0)
	v_mfma_f32_32x32x16_bf16 v[16:31], v[76:79], v[110:113], v[16:31]
	s_cbranch_vccnz .LBB0_145
	s_nop 10
	v_add_f32_e32 v34, v0, v16
	s_lshl_b32 s18, s88, 2
	s_add_u32 s18, s12, s18
	v_add_f32_dpp v34, v34, v34 row_ror:8 row_mask:0xf bank_mask:0xf bound_ctrl:1
	s_addc_u32 s19, s13, 0
	s_add_u32 s12, s6, 0x2c00000
	v_add_f32_dpp v34, v34, v34 row_ror:4 row_mask:0xf bank_mask:0xf bound_ctrl:1
	s_addc_u32 s13, s7, 0
	v_or_b32_e32 v36, v222, v65
	v_add_f32_dpp v34, v34, v34 row_ror:2 row_mask:0xf bank_mask:0xf bound_ctrl:1
	v_lshlrev_b32_e32 v32, 2, v36
	global_load_dword v39, v32, s[18:19]
	global_load_dword v38, v32, s[18:19] offset:128
	v_add_f32_dpp v34, v34, v34 row_ror:1 row_mask:0xf bank_mask:0xf bound_ctrl:1
	v_mov_b32_e32 v35, v34
	s_nop 1
	v_permlane16_swap_b32_e32 v34, v35
	v_add_f32_e32 v34, v34, v35
	v_fmamk_f32 v41, v34, 0xbc800000, v0
	v_fmamk_f32 v0, v34, 0xbc800000, v16
	v_mul_f32_e32 v16, v0, v0
	v_fmac_f32_e32 v16, v41, v41
	v_lshlrev_b32_e32 v152, 2, v223
	v_ashrrev_i32_e32 v67, 31, v66
	v_add_f32_dpp v16, v16, v16 row_ror:8 row_mask:0xf bank_mask:0xf bound_ctrl:1
	v_lshl_add_u64 v[32:33], v[68:69], 0, v[66:67]
	v_lshlrev_b32_e32 v126, 1, v36
	v_mov_b32_e32 v124, v152
	v_mov_b32_e32 v125, v153
	v_lshl_add_u64 v[124:125], v[32:33], 0, v[124:125]
	v_lshlrev_b64 v[124:125], 11, v[124:125]
	v_or_b32_e32 v124, v124, v126
	v_lshl_add_u64 v[124:125], s[10:11], 0, v[124:125]
	global_load_ushort v90, v[124:125], off offset:1536
	global_load_ushort v91, v[124:125], off offset:1600
	v_or_b32_e32 v124, 1, v152
	v_mov_b32_e32 v125, v153
	v_lshl_add_u64 v[124:125], v[32:33], 0, v[124:125]
	v_lshlrev_b64 v[124:125], 11, v[124:125]
	v_or_b32_e32 v124, v124, v126
	v_lshl_add_u64 v[124:125], s[10:11], 0, v[124:125]
	global_load_ushort v92, v[124:125], off offset:1536
	global_load_ushort v93, v[124:125], off offset:1600
	v_or_b32_e32 v124, 2, v152
	v_mov_b32_e32 v125, v153
	v_lshl_add_u64 v[124:125], v[32:33], 0, v[124:125]
	v_lshlrev_b64 v[124:125], 11, v[124:125]
	v_or_b32_e32 v124, v124, v126
	v_lshl_add_u64 v[124:125], s[10:11], 0, v[124:125]
	global_load_ushort v94, v[124:125], off offset:1536
	global_load_ushort v95, v[124:125], off offset:1600
	v_or_b32_e32 v124, 3, v152
	v_mov_b32_e32 v125, v153
	v_lshl_add_u64 v[124:125], v[32:33], 0, v[124:125]
	v_lshlrev_b64 v[124:125], 11, v[124:125]
	v_or_b32_e32 v124, v124, v126
	v_lshl_add_u64 v[124:125], s[10:11], 0, v[124:125]
	global_load_ushort v96, v[124:125], off offset:1536
	global_load_ushort v97, v[124:125], off offset:1600
	v_or_b32_e32 v124, 8, v152
	v_mov_b32_e32 v125, v153
	v_lshl_add_u64 v[124:125], v[32:33], 0, v[124:125]
	v_lshlrev_b64 v[124:125], 11, v[124:125]
	v_or_b32_e32 v124, v124, v126
; #define LAUNDER_V(x) asm volatile("" : "+v"(x))
; __device__ __forceinline__ float bf2f(unsigned short u) { return __uint_as_float(((unsigned)u) << 16); }
; __device__ __forceinline__ float half_sum(float v) { v = row16_allsum(v); v = rows_pair_sum(v); return v; }
; __device__ __forceinline__ int crow(int r, int hi) { return (r & 3) + 8 * (r >> 2) + 4 * hi; }
; __device__ __forceinline__ void ret_out(const Params& P, int l, unsigned char* lds, int u, int tid) {
;     ...
;     const float g0 = gn[h * 64 + r32], g1 = gn[h * 64 + 32 + r32];
;     int c0f = c0; LAUNDER_V(c0f);
; #pragma unroll
;     for (int r = 0; r < 16; ++r) {
;         const float mean = half_sum(o0[r] + o1[r]) * (1.0f / 64.0f);
;         const float d0 = o0[r] - mean, d1 = o1[r] - mean;
;         const float var = half_sum(d0 * d0 + d1 * d1) * (1.0f / 64.0f);
;         const float rstd = 1.0f / sqrtf(var + 1e-5f);
;         const size_t t = tc + c0f + crow(r, hi);
;         const float ga = bf2f(ZR[t * 1024 + 768 + h * 64 + r32]), gb = bf2f(ZR[t * 1024 + 768 + h * 64 + 32 + r32]);
	v_lshl_add_u64 v[124:125], s[10:11], 0, v[124:125]
	global_load_ushort v98, v[124:125], off offset:1536
	global_load_ushort v99, v[124:125], off offset:1600
	v_or_b32_e32 v124, 9, v152
	v_mov_b32_e32 v125, v153
	v_lshl_add_u64 v[124:125], v[32:33], 0, v[124:125]
	v_lshlrev_b64 v[124:125], 11, v[124:125]
	v_or_b32_e32 v124, v124, v126
	v_lshl_add_u64 v[124:125], s[10:11], 0, v[124:125]
	global_load_ushort v100, v[124:125], off offset:1536
	global_load_ushort v101, v[124:125], off offset:1600
	v_or_b32_e32 v124, 10, v152
	v_mov_b32_e32 v125, v153
	v_lshl_add_u64 v[124:125], v[32:33], 0, v[124:125]
	v_lshlrev_b64 v[124:125], 11, v[124:125]
	v_or_b32_e32 v124, v124, v126
	v_lshl_add_u64 v[124:125], s[10:11], 0, v[124:125]
	global_load_ushort v102, v[124:125], off offset:1536
	global_load_ushort v103, v[124:125], off offset:1600
	v_or_b32_e32 v124, 11, v152
	v_mov_b32_e32 v125, v153
	v_lshl_add_u64 v[124:125], v[32:33], 0, v[124:125]
	v_lshlrev_b64 v[124:125], 11, v[124:125]
	v_or_b32_e32 v124, v124, v126
	v_lshl_add_u64 v[124:125], s[10:11], 0, v[124:125]
	global_load_ushort v104, v[124:125], off offset:1536
	global_load_ushort v105, v[124:125], off offset:1600
	v_or_b32_e32 v124, 16, v152
	v_mov_b32_e32 v125, v153
	v_lshl_add_u64 v[124:125], v[32:33], 0, v[124:125]
	v_lshlrev_b64 v[124:125], 11, v[124:125]
	v_or_b32_e32 v124, v124, v126
	v_lshl_add_u64 v[124:125], s[10:11], 0, v[124:125]
	global_load_ushort v106, v[124:125], off offset:1536
	global_load_ushort v107, v[124:125], off offset:1600
	v_or_b32_e32 v124, 17, v152
	v_mov_b32_e32 v125, v153
	v_lshl_add_u64 v[124:125], v[32:33], 0, v[124:125]
	v_lshlrev_b64 v[124:125], 11, v[124:125]
	v_or_b32_e32 v124, v124, v126
	v_lshl_add_u64 v[124:125], s[10:11], 0, v[124:125]
	global_load_ushort v108, v[124:125], off offset:1536
	global_load_ushort v109, v[124:125], off offset:1600
	v_or_b32_e32 v124, 18, v152
	v_mov_b32_e32 v125, v153
	v_lshl_add_u64 v[124:125], v[32:33], 0, v[124:125]
	v_lshlrev_b64 v[124:125], 11, v[124:125]
	v_or_b32_e32 v124, v124, v126
	v_lshl_add_u64 v[124:125], s[10:11], 0, v[124:125]
	global_load_ushort v110, v[124:125], off offset:1536
	global_load_ushort v111, v[124:125], off offset:1600
	v_or_b32_e32 v124, 19, v152
	v_mov_b32_e32 v125, v153
	v_lshl_add_u64 v[124:125], v[32:33], 0, v[124:125]
	v_lshlrev_b64 v[124:125], 11, v[124:125]
	v_or_b32_e32 v124, v124, v126
	v_lshl_add_u64 v[124:125], s[10:11], 0, v[124:125]
	global_load_ushort v112, v[124:125], off offset:1536
	global_load_ushort v113, v[124:125], off offset:1600
	v_or_b32_e32 v124, 24, v152
	v_mov_b32_e32 v125, v153
	v_lshl_add_u64 v[124:125], v[32:33], 0, v[124:125]
	v_lshlrev_b64 v[124:125], 11, v[124:125]
	v_or_b32_e32 v124, v124, v126
	v_lshl_add_u64 v[124:125], s[10:11], 0, v[124:125]
	global_load_ushort v114, v[124:125], off offset:1536
	global_load_ushort v115, v[124:125], off offset:1600
	v_or_b32_e32 v124, 25, v152
	v_mov_b32_e32 v125, v153
	v_lshl_add_u64 v[124:125], v[32:33], 0, v[124:125]
	v_lshlrev_b64 v[124:125], 11, v[124:125]
	v_or_b32_e32 v124, v124, v126
	v_lshl_add_u64 v[124:125], s[10:11], 0, v[124:125]
	global_load_ushort v116, v[124:125], off offset:1536
	global_load_ushort v117, v[124:125], off offset:1600
	v_or_b32_e32 v124, 26, v152
	v_mov_b32_e32 v125, v153
	v_lshl_add_u64 v[124:125], v[32:33], 0, v[124:125]
	v_lshlrev_b64 v[124:125], 11, v[124:125]
	v_or_b32_e32 v124, v124, v126
	v_lshl_add_u64 v[124:125], s[10:11], 0, v[124:125]
	global_load_ushort v118, v[124:125], off offset:1536
	global_load_ushort v119, v[124:125], off offset:1600
	v_or_b32_e32 v124, 27, v152
	v_mov_b32_e32 v125, v153
	v_lshl_add_u64 v[124:125], v[32:33], 0, v[124:125]
	v_lshlrev_b64 v[124:125], 11, v[124:125]
	v_or_b32_e32 v124, v124, v126
	v_lshl_add_u64 v[124:125], s[10:11], 0, v[124:125]
	global_load_ushort v120, v[124:125], off offset:1536
	global_load_ushort v121, v[124:125], off offset:1600
	s_nop 0
	v_add_f32_dpp v16, v16, v16 row_ror:4 row_mask:0xf bank_mask:0xf bound_ctrl:1
	s_nop 1
	v_add_f32_dpp v16, v16, v16 row_ror:2 row_mask:0xf bank_mask:0xf bound_ctrl:1
	s_nop 1
	v_add_f32_dpp v16, v16, v16 row_ror:1 row_mask:0xf bank_mask:0xf bound_ctrl:1
	v_mov_b32_e32 v34, v16
	s_nop 1
	v_permlane16_swap_b32_e32 v16, v34
	v_add_f32_e32 v16, v16, v34
	v_fmamk_f32 v16, v16, 0x3c800000, v200
	v_cmp_gt_f32_e32 vcc, s43, v16
	v_mul_f32_e32 v34, 0x4f800000, v16
	s_nop 0
	v_cndmask_b32_e32 v16, v16, v34, vcc
	v_sqrt_f32_e32 v34, v16
	s_nop 0
	v_add_u32_e32 v35, -1, v34
	v_fma_f32 v37, -v35, v34, v16
	v_cmp_ge_f32_e64 s[6:7], 0, v37
	v_add_u32_e32 v37, 1, v34
	s_nop 0
	v_cndmask_b32_e64 v35, v34, v35, s[6:7]
	v_fma_f32 v34, -v37, v34, v16
	v_cmp_lt_f32_e64 s[6:7], 0, v34
	s_nop 1
	v_cndmask_b32_e64 v34, v35, v37, s[6:7]
	v_mul_f32_e32 v35, 0x37800000, v34
	v_cndmask_b32_e32 v34, v34, v35, vcc
	v_cmp_class_f32_e32 vcc, v16, v175
	s_nop 1
	v_cndmask_b32_e32 v16, v34, v16, vcc
	v_div_scale_f32 v34, s[6:7], v16, v16, 1.0
	v_rcp_f32_e32 v35, v34
	s_nop 0
	v_fma_f32 v37, -v34, v35, 1.0
	v_fmac_f32_e32 v35, v37, v35
	v_div_scale_f32 v37, vcc, 1.0, v16, 1.0
	v_mul_f32_e32 v40, v37, v35
	v_fma_f32 v42, -v34, v40, v37
	v_fmac_f32_e32 v40, v42, v35
	v_fma_f32 v34, -v34, v40, v37
	v_div_fmas_f32 v34, v34, v35, v40
	v_div_fixup_f32 v16, v34, v16, 1.0
	v_lshl_add_u64 v[34:35], v[32:33], 0, v[152:153]
	v_lshlrev_b64 v[34:35], 11, v[34:35]
	v_lshlrev_b32_e32 v40, 1, v36
	v_or_b32_e32 v42, v34, v40
	v_or_b32_e32 v34, 0x600, v42
	v_lshl_add_u64 v[36:37], s[10:11], 0, v[34:35]
	s_nop 0
	v_mov_b32_e32 v37, v35
	v_lshl_add_u64 v[34:35], s[12:13], 0, v[34:35]
	s_waitcnt vmcnt(0)
; __device__ __forceinline__ unsigned pk2(float lo, float hi) { return pg8::pk_bf16_rne(lo, hi); }
; __device__ __forceinline__ float bf2f(unsigned short u) { return __uint_as_float(((unsigned)u) << 16); }
; __device__ __forceinline__ float half_sum(float v) { v = row16_allsum(v); v = rows_pair_sum(v); return v; }
; __device__ __forceinline__ int crow(int r, int hi) { return (r & 3) + 8 * (r >> 2) + 4 * hi; }
; __device__ __forceinline__ void ret_out(const Params& P, int l, unsigned char* lds, int u, int tid) {
;     ...
;     for (int r = 0; r < 16; ++r) {
;         const float mean = half_sum(o0[r] + o1[r]) * (1.0f / 64.0f);
;         const float d0 = o0[r] - mean, d1 = o1[r] - mean;
;         const float var = half_sum(d0 * d0 + d1 * d1) * (1.0f / 64.0f);
;         const float rstd = 1.0f / sqrtf(var + 1e-5f);
;         const size_t t = tc + c0f + crow(r, hi);
;         const float ga = bf2f(ZR[t * 1024 + 768 + h * 64 + r32]), gb = bf2f(ZR[t * 1024 + 768 + h * 64 + 32 + r32]);
;         const float sa = ga / (1.0f + __expf(-ga)), sb = gb / (1.0f + __expf(-gb));
;         MIX[t * 1024 + 768 + h * 64 + r32] = (bf16_t)(pk2(sa * d0 * rstd * g0, 0.f) & 0xffffu);
;         MIX[t * 1024 + 768 + h * 64 + 32 + r32] = (bf16_t)(pk2(sb * d1 * rstd * g1, 0.f) & 0xffffu);
	v_lshlrev_b32_e32 v44, 16, v90
	v_or_b32_e32 v36, 0x640, v42
	v_lshl_add_u64 v[42:43], s[10:11], 0, v[36:37]
	s_nop 0
	v_mul_f32_e32 v43, 0xbfb8aa3b, v44
	v_exp_f32_e32 v43, v43
	v_lshlrev_b32_e32 v42, 16, v91
	v_add_f32_e32 v43, 1.0, v43
	v_div_scale_f32 v45, s[6:7], v43, v43, v44
	v_rcp_f32_e32 v46, v45
	s_nop 0
	v_fma_f32 v47, -v45, v46, 1.0
	v_fmac_f32_e32 v46, v47, v46
	v_div_scale_f32 v47, vcc, v44, v43, v44
	v_mul_f32_e32 v48, v47, v46
	v_fma_f32 v49, -v45, v48, v47
	v_fmac_f32_e32 v48, v49, v46
	v_fma_f32 v45, -v45, v48, v47
	v_div_fmas_f32 v45, v45, v46, v48
	v_div_fixup_f32 v43, v45, v43, v44
	v_mul_f32_e32 v44, 0xbfb8aa3b, v42
	v_exp_f32_e32 v44, v44
	v_mul_f32_e32 v41, v41, v43
	v_mul_f32_e32 v41, v16, v41
	v_mul_f32_e32 v41, v39, v41
	v_add_f32_e32 v44, 1.0, v44
	v_div_scale_f32 v45, s[6:7], v44, v44, v42
	v_rcp_f32_e32 v46, v45
	v_cvt_pk_bf16_f32 v41, v41, s0
	global_store_short v[34:35], v41, off
	v_lshl_add_u64 v[34:35], s[12:13], 0, v[36:37]
	v_fma_f32 v47, -v45, v46, 1.0
	v_fmac_f32_e32 v46, v47, v46
	v_div_scale_f32 v47, vcc, v42, v44, v42
	v_mul_f32_e32 v48, v47, v46
	v_fma_f32 v49, -v45, v48, v47
	v_fmac_f32_e32 v48, v49, v46
	v_fma_f32 v45, -v45, v48, v47
	v_div_fmas_f32 v45, v45, v46, v48
	v_div_fixup_f32 v42, v45, v44, v42
	v_mul_f32_e32 v0, v0, v42
	v_mul_f32_e32 v0, v16, v0
	v_mul_f32_e32 v0, v38, v0
	v_cvt_pk_bf16_f32 v0, v0, s0
	global_store_short v[34:35], v0, off
	v_add_f32_e32 v0, v1, v17
	s_nop 1
	v_add_f32_dpp v0, v0, v0 row_ror:8 row_mask:0xf bank_mask:0xf bound_ctrl:1
	s_nop 1
	v_add_f32_dpp v0, v0, v0 row_ror:4 row_mask:0xf bank_mask:0xf bound_ctrl:1
	s_nop 1
	v_add_f32_dpp v0, v0, v0 row_ror:2 row_mask:0xf bank_mask:0xf bound_ctrl:1
	s_nop 1
	v_add_f32_dpp v0, v0, v0 row_ror:1 row_mask:0xf bank_mask:0xf bound_ctrl:1
	v_mov_b32_e32 v16, v0
	s_nop 1
	v_permlane16_swap_b32_e32 v0, v16
	v_add_f32_e32 v0, v0, v16
	v_fmamk_f32 v34, v0, 0xbc800000, v17
	v_fmamk_f32 v35, v0, 0xbc800000, v1
	v_mul_f32_e32 v0, v34, v34
	v_fmac_f32_e32 v0, v35, v35
	s_nop 1
	v_add_f32_dpp v0, v0, v0 row_ror:8 row_mask:0xf bank_mask:0xf bound_ctrl:1
	s_nop 1
	v_add_f32_dpp v0, v0, v0 row_ror:4 row_mask:0xf bank_mask:0xf bound_ctrl:1
	s_nop 1
	v_add_f32_dpp v0, v0, v0 row_ror:2 row_mask:0xf bank_mask:0xf bound_ctrl:1
	s_nop 1
	v_add_f32_dpp v0, v0, v0 row_ror:1 row_mask:0xf bank_mask:0xf bound_ctrl:1
	v_mov_b32_e32 v1, v0
	s_nop 1
	v_permlane16_swap_b32_e32 v0, v1
	v_add_f32_e32 v0, v0, v1
	v_fmamk_f32 v0, v0, 0x3c800000, v200
	v_cmp_gt_f32_e32 vcc, s43, v0
	v_mul_f32_e32 v1, 0x4f800000, v0
	s_nop 0
	v_cndmask_b32_e32 v0, v0, v1, vcc
	v_sqrt_f32_e32 v1, v0
	s_nop 0
	v_add_u32_e32 v16, -1, v1
	v_fma_f32 v17, -v16, v1, v0
	v_cmp_ge_f32_e64 s[6:7], 0, v17
	v_add_u32_e32 v17, 1, v1
	s_nop 0
	v_cndmask_b32_e64 v16, v1, v16, s[6:7]
	v_fma_f32 v1, -v17, v1, v0
	v_cmp_lt_f32_e64 s[6:7], 0, v1
	s_nop 1
	v_cndmask_b32_e64 v1, v16, v17, s[6:7]
	v_mul_f32_e32 v16, 0x37800000, v1
	v_cndmask_b32_e32 v1, v1, v16, vcc
	v_cmp_class_f32_e32 vcc, v0, v175
	s_nop 1
	v_cndmask_b32_e32 v0, v1, v0, vcc
	v_div_scale_f32 v1, s[6:7], v0, v0, 1.0
	v_rcp_f32_e32 v16, v1
	s_nop 0
	v_fma_f32 v17, -v1, v16, 1.0
	v_fmac_f32_e32 v16, v17, v16
	v_div_scale_f32 v17, vcc, 1.0, v0, 1.0
	v_mul_f32_e32 v36, v17, v16
	v_fma_f32 v37, -v1, v36, v17
	v_fmac_f32_e32 v36, v37, v16
	v_fma_f32 v1, -v1, v36, v17
	v_div_fmas_f32 v1, v1, v16, v36
	v_div_fixup_f32 v36, v1, v0, 1.0
	v_or_b32_e32 v0, 1, v152
	v_mov_b32_e32 v1, v153
	v_lshl_add_u64 v[0:1], v[32:33], 0, v[0:1]
	v_lshlrev_b64 v[0:1], 11, v[0:1]
	v_or_b32_e32 v37, v0, v40
	v_or_b32_e32 v0, 0x600, v37
	v_lshl_add_u64 v[16:17], s[10:11], 0, v[0:1]
	s_nop 0
	v_mov_b32_e32 v17, v1
	v_lshl_add_u64 v[0:1], s[12:13], 0, v[0:1]
	v_lshlrev_b32_e32 v41, 16, v92
	v_or_b32_e32 v16, 0x640, v37
	v_lshl_add_u64 v[42:43], s[10:11], 0, v[16:17]
	s_nop 0
	v_mul_f32_e32 v42, 0xbfb8aa3b, v41
	v_exp_f32_e32 v42, v42
	v_lshlrev_b32_e32 v37, 16, v93
	v_add_f32_e32 v42, 1.0, v42
	v_div_scale_f32 v43, s[6:7], v42, v42, v41
	v_rcp_f32_e32 v44, v43
	s_nop 0
	v_fma_f32 v45, -v43, v44, 1.0
	v_fmac_f32_e32 v44, v45, v44
	v_div_scale_f32 v45, vcc, v41, v42, v41
	v_mul_f32_e32 v46, v45, v44
	v_fma_f32 v47, -v43, v46, v45
	v_fmac_f32_e32 v46, v47, v44
	v_fma_f32 v43, -v43, v46, v45
	v_div_fmas_f32 v43, v43, v44, v46
	v_div_fixup_f32 v41, v43, v42, v41
	v_mul_f32_e32 v42, 0xbfb8aa3b, v37
	v_exp_f32_e32 v42, v42
	v_mul_f32_e32 v35, v35, v41
	v_mul_f32_e32 v35, v36, v35
	v_mul_f32_e32 v35, v39, v35
	v_add_f32_e32 v42, 1.0, v42
	v_div_scale_f32 v43, s[6:7], v42, v42, v37
	v_rcp_f32_e32 v44, v43
	v_cvt_pk_bf16_f32 v35, v35, s0
	global_store_short v[0:1], v35, off
	v_fma_f32 v45, -v43, v44, 1.0
	v_fmac_f32_e32 v44, v45, v44
	v_div_scale_f32 v45, vcc, v37, v42, v37
	v_mul_f32_e32 v46, v45, v44
	v_fma_f32 v47, -v43, v46, v45
	v_fmac_f32_e32 v46, v47, v44
	v_fma_f32 v43, -v43, v46, v45
	v_div_fmas_f32 v43, v43, v44, v46
	v_div_fixup_f32 v37, v43, v42, v37
	v_mul_f32_e32 v0, v34, v37
	v_mul_f32_e32 v0, v36, v0
	v_mul_f32_e32 v0, v38, v0
	v_cvt_pk_bf16_f32 v34, v0, s0
	v_lshl_add_u64 v[0:1], s[12:13], 0, v[16:17]
	global_store_short v[0:1], v34, off
	v_add_f32_e32 v0, v2, v18
	s_nop 1
	v_add_f32_dpp v0, v0, v0 row_ror:8 row_mask:0xf bank_mask:0xf bound_ctrl:1
	s_nop 1
	v_add_f32_dpp v0, v0, v0 row_ror:4 row_mask:0xf bank_mask:0xf bound_ctrl:1
	s_nop 1
	v_add_f32_dpp v0, v0, v0 row_ror:2 row_mask:0xf bank_mask:0xf bound_ctrl:1
	s_nop 1
	v_add_f32_dpp v0, v0, v0 row_ror:1 row_mask:0xf bank_mask:0xf bound_ctrl:1
	v_mov_b32_e32 v1, v0
	s_nop 1
	v_permlane16_swap_b32_e32 v0, v1
	v_add_f32_e32 v0, v0, v1
	v_fmamk_f32 v34, v0, 0xbc800000, v2
	v_fmamk_f32 v2, v0, 0xbc800000, v18
; __device__ __forceinline__ unsigned pk2(float lo, float hi) { return pg8::pk_bf16_rne(lo, hi); }
; __device__ __forceinline__ float bf2f(unsigned short u) { return __uint_as_float(((unsigned)u) << 16); }
; __device__ __forceinline__ float half_sum(float v) { v = row16_allsum(v); v = rows_pair_sum(v); return v; }
; __device__ __forceinline__ int crow(int r, int hi) { return (r & 3) + 8 * (r >> 2) + 4 * hi; }
; __device__ __forceinline__ void ret_out(const Params& P, int l, unsigned char* lds, int u, int tid) {
;     ...
;     for (int r = 0; r < 16; ++r) {
;         const float mean = half_sum(o0[r] + o1[r]) * (1.0f / 64.0f);
;         const float d0 = o0[r] - mean, d1 = o1[r] - mean;
;         const float var = half_sum(d0 * d0 + d1 * d1) * (1.0f / 64.0f);
;         const float rstd = 1.0f / sqrtf(var + 1e-5f);
;         const size_t t = tc + c0f + crow(r, hi);
;         const float ga = bf2f(ZR[t * 1024 + 768 + h * 64 + r32]), gb = bf2f(ZR[t * 1024 + 768 + h * 64 + 32 + r32]);
;         const float sa = ga / (1.0f + __expf(-ga)), sb = gb / (1.0f + __expf(-gb));
;         MIX[t * 1024 + 768 + h * 64 + r32] = (bf16_t)(pk2(sa * d0 * rstd * g0, 0.f) & 0xffffu);
;         MIX[t * 1024 + 768 + h * 64 + 32 + r32] = (bf16_t)(pk2(sb * d1 * rstd * g1, 0.f) & 0xffffu);
	v_mul_f32_e32 v0, v2, v2
	v_fmac_f32_e32 v0, v34, v34
	s_nop 1
	v_add_f32_dpp v0, v0, v0 row_ror:8 row_mask:0xf bank_mask:0xf bound_ctrl:1
	s_nop 1
	v_add_f32_dpp v0, v0, v0 row_ror:4 row_mask:0xf bank_mask:0xf bound_ctrl:1
	s_nop 1
	v_add_f32_dpp v0, v0, v0 row_ror:2 row_mask:0xf bank_mask:0xf bound_ctrl:1
	s_nop 1
	v_add_f32_dpp v0, v0, v0 row_ror:1 row_mask:0xf bank_mask:0xf bound_ctrl:1
	v_mov_b32_e32 v1, v0
	s_nop 1
	v_permlane16_swap_b32_e32 v0, v1
	v_add_f32_e32 v0, v0, v1
	v_fmamk_f32 v0, v0, 0x3c800000, v200
	v_cmp_gt_f32_e32 vcc, s43, v0
	v_mul_f32_e32 v1, 0x4f800000, v0
	s_nop 0
	v_cndmask_b32_e32 v0, v0, v1, vcc
	v_sqrt_f32_e32 v1, v0
	s_nop 0
	v_add_u32_e32 v16, -1, v1
	v_fma_f32 v17, -v16, v1, v0
	v_cmp_ge_f32_e64 s[6:7], 0, v17
	v_add_u32_e32 v17, 1, v1
	s_nop 0
	v_cndmask_b32_e64 v16, v1, v16, s[6:7]
	v_fma_f32 v1, -v17, v1, v0
	v_cmp_lt_f32_e64 s[6:7], 0, v1
	s_nop 1
	v_cndmask_b32_e64 v1, v16, v17, s[6:7]
	v_mul_f32_e32 v16, 0x37800000, v1
	v_cndmask_b32_e32 v1, v1, v16, vcc
	v_cmp_class_f32_e32 vcc, v0, v175
	s_nop 1
	v_cndmask_b32_e32 v0, v1, v0, vcc
	v_div_scale_f32 v1, s[6:7], v0, v0, 1.0
	v_rcp_f32_e32 v16, v1
	s_nop 0
	v_fma_f32 v17, -v1, v16, 1.0
	v_fmac_f32_e32 v16, v17, v16
	v_div_scale_f32 v17, vcc, 1.0, v0, 1.0
	v_mul_f32_e32 v18, v17, v16
	v_fma_f32 v35, -v1, v18, v17
	v_fmac_f32_e32 v18, v35, v16
	v_fma_f32 v1, -v1, v18, v17
	v_div_fmas_f32 v1, v1, v16, v18
	v_div_fixup_f32 v18, v1, v0, 1.0
	v_or_b32_e32 v0, 2, v152
	v_mov_b32_e32 v1, v153
	v_lshl_add_u64 v[0:1], v[32:33], 0, v[0:1]
	v_lshlrev_b64 v[0:1], 11, v[0:1]
	v_or_b32_e32 v35, v0, v40
	v_or_b32_e32 v0, 0x600, v35
	v_lshl_add_u64 v[16:17], s[10:11], 0, v[0:1]
	s_nop 0
	v_mov_b32_e32 v17, v1
	v_lshl_add_u64 v[0:1], s[12:13], 0, v[0:1]
	v_lshlrev_b32_e32 v41, 16, v94
	v_or_b32_e32 v16, 0x640, v35
	v_lshl_add_u64 v[36:37], s[10:11], 0, v[16:17]
	s_nop 0
	v_mul_f32_e32 v36, 0xbfb8aa3b, v41
	v_exp_f32_e32 v36, v36
	v_lshlrev_b32_e32 v35, 16, v95
	v_add_f32_e32 v36, 1.0, v36
	v_div_scale_f32 v37, s[6:7], v36, v36, v41
	v_rcp_f32_e32 v42, v37
	s_nop 0
	v_fma_f32 v43, -v37, v42, 1.0
	v_fmac_f32_e32 v42, v43, v42
	v_div_scale_f32 v43, vcc, v41, v36, v41
	v_mul_f32_e32 v44, v43, v42
	v_fma_f32 v45, -v37, v44, v43
	v_fmac_f32_e32 v44, v45, v42
	v_fma_f32 v37, -v37, v44, v43
	v_div_fmas_f32 v37, v37, v42, v44
	v_div_fixup_f32 v36, v37, v36, v41
	v_mul_f32_e32 v37, 0xbfb8aa3b, v35
	v_exp_f32_e32 v37, v37
	v_mul_f32_e32 v34, v34, v36
	v_mul_f32_e32 v34, v18, v34
	v_mul_f32_e32 v34, v39, v34
	v_add_f32_e32 v37, 1.0, v37
	v_div_scale_f32 v41, s[6:7], v37, v37, v35
	v_rcp_f32_e32 v42, v41
	v_cvt_pk_bf16_f32 v34, v34, s0
	global_store_short v[0:1], v34, off
	v_fma_f32 v43, -v41, v42, 1.0
	v_fmac_f32_e32 v42, v43, v42
	v_div_scale_f32 v43, vcc, v35, v37, v35
	v_mul_f32_e32 v44, v43, v42
	v_fma_f32 v45, -v41, v44, v43
	v_fmac_f32_e32 v44, v45, v42
	v_fma_f32 v41, -v41, v44, v43
	v_div_fmas_f32 v41, v41, v42, v44
	v_div_fixup_f32 v35, v41, v37, v35
	v_mul_f32_e32 v0, v2, v35
	v_mul_f32_e32 v0, v18, v0
	v_mul_f32_e32 v0, v38, v0
	v_cvt_pk_bf16_f32 v2, v0, s0
	v_lshl_add_u64 v[0:1], s[12:13], 0, v[16:17]
	global_store_short v[0:1], v2, off
	v_add_f32_e32 v0, v3, v19
	s_nop 1
	v_add_f32_dpp v0, v0, v0 row_ror:8 row_mask:0xf bank_mask:0xf bound_ctrl:1
	s_nop 1
	v_add_f32_dpp v0, v0, v0 row_ror:4 row_mask:0xf bank_mask:0xf bound_ctrl:1
	s_nop 1
	v_add_f32_dpp v0, v0, v0 row_ror:2 row_mask:0xf bank_mask:0xf bound_ctrl:1
	s_nop 1
	v_add_f32_dpp v0, v0, v0 row_ror:1 row_mask:0xf bank_mask:0xf bound_ctrl:1
	v_mov_b32_e32 v1, v0
	s_nop 1
	v_permlane16_swap_b32_e32 v0, v1
	v_add_f32_e32 v0, v0, v1
	v_fmamk_f32 v16, v0, 0xbc800000, v19
	v_fmamk_f32 v17, v0, 0xbc800000, v3
	v_mul_f32_e32 v0, v16, v16
	v_fmac_f32_e32 v0, v17, v17
	s_nop 1
	v_add_f32_dpp v0, v0, v0 row_ror:8 row_mask:0xf bank_mask:0xf bound_ctrl:1
	s_nop 1
	v_add_f32_dpp v0, v0, v0 row_ror:4 row_mask:0xf bank_mask:0xf bound_ctrl:1
	s_nop 1
	v_add_f32_dpp v0, v0, v0 row_ror:2 row_mask:0xf bank_mask:0xf bound_ctrl:1
	s_nop 1
	v_add_f32_dpp v0, v0, v0 row_ror:1 row_mask:0xf bank_mask:0xf bound_ctrl:1
	v_mov_b32_e32 v1, v0
	s_nop 1
	v_permlane16_swap_b32_e32 v0, v1
	v_add_f32_e32 v0, v0, v1
	v_fmamk_f32 v0, v0, 0x3c800000, v200
	v_cmp_gt_f32_e32 vcc, s43, v0
	v_mul_f32_e32 v1, 0x4f800000, v0
	s_nop 0
	v_cndmask_b32_e32 v0, v0, v1, vcc
	v_sqrt_f32_e32 v1, v0
	s_nop 0
	v_add_u32_e32 v2, -1, v1
	v_fma_f32 v3, -v2, v1, v0
	v_cmp_ge_f32_e64 s[6:7], 0, v3
	v_add_u32_e32 v3, 1, v1
	s_nop 0
	v_cndmask_b32_e64 v2, v1, v2, s[6:7]
	v_fma_f32 v1, -v3, v1, v0
	v_cmp_lt_f32_e64 s[6:7], 0, v1
	s_nop 1
	v_cndmask_b32_e64 v1, v2, v3, s[6:7]
	v_mul_f32_e32 v2, 0x37800000, v1
	v_cndmask_b32_e32 v1, v1, v2, vcc
	v_cmp_class_f32_e32 vcc, v0, v175
	s_nop 1
	v_cndmask_b32_e32 v0, v1, v0, vcc
	v_div_scale_f32 v1, s[6:7], v0, v0, 1.0
	v_rcp_f32_e32 v2, v1
	s_nop 0
	v_fma_f32 v3, -v1, v2, 1.0
	v_fmac_f32_e32 v2, v3, v2
	v_div_scale_f32 v3, vcc, 1.0, v0, 1.0
	v_mul_f32_e32 v18, v3, v2
	v_fma_f32 v19, -v1, v18, v3
	v_fmac_f32_e32 v18, v19, v2
	v_fma_f32 v1, -v1, v18, v3
	v_div_fmas_f32 v1, v1, v2, v18
	v_div_fixup_f32 v18, v1, v0, 1.0
	v_or_b32_e32 v0, 3, v152
	v_mov_b32_e32 v1, v153
	v_lshl_add_u64 v[0:1], v[32:33], 0, v[0:1]
	v_lshlrev_b64 v[0:1], 11, v[0:1]
	v_or_b32_e32 v19, v0, v40
	v_or_b32_e32 v0, 0x600, v19
	v_lshl_add_u64 v[2:3], s[10:11], 0, v[0:1]
	s_nop 0
	v_mov_b32_e32 v3, v1
	v_lshl_add_u64 v[0:1], s[12:13], 0, v[0:1]
	v_lshlrev_b32_e32 v36, 16, v96
	v_or_b32_e32 v2, 0x640, v19
	v_lshl_add_u64 v[34:35], s[10:11], 0, v[2:3]
	s_nop 0
	v_mul_f32_e32 v34, 0xbfb8aa3b, v36
	v_exp_f32_e32 v34, v34
	v_lshlrev_b32_e32 v19, 16, v97
; __device__ __forceinline__ unsigned pk2(float lo, float hi) { return pg8::pk_bf16_rne(lo, hi); }
; __device__ __forceinline__ float bf2f(unsigned short u) { return __uint_as_float(((unsigned)u) << 16); }
; __device__ __forceinline__ float half_sum(float v) { v = row16_allsum(v); v = rows_pair_sum(v); return v; }
; __device__ __forceinline__ int crow(int r, int hi) { return (r & 3) + 8 * (r >> 2) + 4 * hi; }
; __device__ __forceinline__ void ret_out(const Params& P, int l, unsigned char* lds, int u, int tid) {
;     ...
;     for (int r = 0; r < 16; ++r) {
;         const float mean = half_sum(o0[r] + o1[r]) * (1.0f / 64.0f);
;         const float d0 = o0[r] - mean, d1 = o1[r] - mean;
;         const float var = half_sum(d0 * d0 + d1 * d1) * (1.0f / 64.0f);
;         const float rstd = 1.0f / sqrtf(var + 1e-5f);
;         const size_t t = tc + c0f + crow(r, hi);
;         const float ga = bf2f(ZR[t * 1024 + 768 + h * 64 + r32]), gb = bf2f(ZR[t * 1024 + 768 + h * 64 + 32 + r32]);
;         const float sa = ga / (1.0f + __expf(-ga)), sb = gb / (1.0f + __expf(-gb));
;         MIX[t * 1024 + 768 + h * 64 + r32] = (bf16_t)(pk2(sa * d0 * rstd * g0, 0.f) & 0xffffu);
;         MIX[t * 1024 + 768 + h * 64 + 32 + r32] = (bf16_t)(pk2(sb * d1 * rstd * g1, 0.f) & 0xffffu);
	v_add_f32_e32 v34, 1.0, v34
	v_div_scale_f32 v35, s[6:7], v34, v34, v36
	v_rcp_f32_e32 v37, v35
	s_nop 0
	v_fma_f32 v41, -v35, v37, 1.0
	v_fmac_f32_e32 v37, v41, v37
	v_div_scale_f32 v41, vcc, v36, v34, v36
	v_mul_f32_e32 v42, v41, v37
	v_fma_f32 v43, -v35, v42, v41
	v_fmac_f32_e32 v42, v43, v37
	v_fma_f32 v35, -v35, v42, v41
	v_div_fmas_f32 v35, v35, v37, v42
	v_div_fixup_f32 v34, v35, v34, v36
	v_mul_f32_e32 v35, 0xbfb8aa3b, v19
	v_exp_f32_e32 v35, v35
	v_mul_f32_e32 v17, v17, v34
	v_mul_f32_e32 v17, v18, v17
	v_mul_f32_e32 v17, v39, v17
	v_add_f32_e32 v35, 1.0, v35
	v_div_scale_f32 v36, s[6:7], v35, v35, v19
	v_rcp_f32_e32 v37, v36
	v_cvt_pk_bf16_f32 v17, v17, s0
	global_store_short v[0:1], v17, off
	v_fma_f32 v41, -v36, v37, 1.0
	v_fmac_f32_e32 v37, v41, v37
	v_div_scale_f32 v41, vcc, v19, v35, v19
	v_mul_f32_e32 v42, v41, v37
	v_fma_f32 v43, -v36, v42, v41
	v_fmac_f32_e32 v42, v43, v37
	v_fma_f32 v36, -v36, v42, v41
	v_div_fmas_f32 v36, v36, v37, v42
	v_div_fixup_f32 v19, v36, v35, v19
	v_mul_f32_e32 v0, v16, v19
	v_mul_f32_e32 v0, v18, v0
	v_mul_f32_e32 v0, v38, v0
	v_cvt_pk_bf16_f32 v16, v0, s0
	v_lshl_add_u64 v[0:1], s[12:13], 0, v[2:3]
	global_store_short v[0:1], v16, off
	v_add_f32_e32 v0, v4, v20
	s_nop 1
	v_add_f32_dpp v0, v0, v0 row_ror:8 row_mask:0xf bank_mask:0xf bound_ctrl:1
	s_nop 1
	v_add_f32_dpp v0, v0, v0 row_ror:4 row_mask:0xf bank_mask:0xf bound_ctrl:1
	s_nop 1
	v_add_f32_dpp v0, v0, v0 row_ror:2 row_mask:0xf bank_mask:0xf bound_ctrl:1
	s_nop 1
	v_add_f32_dpp v0, v0, v0 row_ror:1 row_mask:0xf bank_mask:0xf bound_ctrl:1
	v_mov_b32_e32 v1, v0
	s_nop 1
	v_permlane16_swap_b32_e32 v0, v1
	v_add_f32_e32 v0, v0, v1
	v_fmamk_f32 v16, v0, 0xbc800000, v4
	v_fmamk_f32 v4, v0, 0xbc800000, v20
	v_mul_f32_e32 v0, v4, v4
	v_fmac_f32_e32 v0, v16, v16
	s_nop 1
	v_add_f32_dpp v0, v0, v0 row_ror:8 row_mask:0xf bank_mask:0xf bound_ctrl:1
	s_nop 1
	v_add_f32_dpp v0, v0, v0 row_ror:4 row_mask:0xf bank_mask:0xf bound_ctrl:1
	s_nop 1
	v_add_f32_dpp v0, v0, v0 row_ror:2 row_mask:0xf bank_mask:0xf bound_ctrl:1
	s_nop 1
	v_add_f32_dpp v0, v0, v0 row_ror:1 row_mask:0xf bank_mask:0xf bound_ctrl:1
	v_mov_b32_e32 v1, v0
	s_nop 1
	v_permlane16_swap_b32_e32 v0, v1
	v_add_f32_e32 v0, v0, v1
	v_fmamk_f32 v0, v0, 0x3c800000, v200
	v_cmp_gt_f32_e32 vcc, s43, v0
	v_mul_f32_e32 v1, 0x4f800000, v0
	s_nop 0
	v_cndmask_b32_e32 v0, v0, v1, vcc
	v_sqrt_f32_e32 v1, v0
	s_nop 0
	v_add_u32_e32 v2, -1, v1
	v_fma_f32 v3, -v2, v1, v0
	v_cmp_ge_f32_e64 s[6:7], 0, v3
	v_add_u32_e32 v3, 1, v1
	s_nop 0
	v_cndmask_b32_e64 v2, v1, v2, s[6:7]
	v_fma_f32 v1, -v3, v1, v0
	v_cmp_lt_f32_e64 s[6:7], 0, v1
	s_nop 1
	v_cndmask_b32_e64 v1, v2, v3, s[6:7]
	v_mul_f32_e32 v2, 0x37800000, v1
	v_cndmask_b32_e32 v1, v1, v2, vcc
	v_cmp_class_f32_e32 vcc, v0, v175
	s_nop 1
	v_cndmask_b32_e32 v0, v1, v0, vcc
	v_div_scale_f32 v1, s[6:7], v0, v0, 1.0
	v_rcp_f32_e32 v2, v1
	s_nop 0
	v_fma_f32 v3, -v1, v2, 1.0
	v_fmac_f32_e32 v2, v3, v2
	v_div_scale_f32 v3, vcc, 1.0, v0, 1.0
	v_mul_f32_e32 v17, v3, v2
	v_fma_f32 v18, -v1, v17, v3
	v_fmac_f32_e32 v17, v18, v2
	v_fma_f32 v1, -v1, v17, v3
	v_div_fmas_f32 v1, v1, v2, v17
	v_div_fixup_f32 v17, v1, v0, 1.0
	v_or_b32_e32 v0, 8, v152
	v_mov_b32_e32 v1, v153
	v_lshl_add_u64 v[0:1], v[32:33], 0, v[0:1]
	v_lshlrev_b64 v[0:1], 11, v[0:1]
	v_or_b32_e32 v18, v0, v40
	v_or_b32_e32 v0, 0x600, v18
	v_lshl_add_u64 v[2:3], s[10:11], 0, v[0:1]
	s_nop 0
	v_mov_b32_e32 v3, v1
	v_lshl_add_u64 v[0:1], s[12:13], 0, v[0:1]
	v_lshlrev_b32_e32 v20, 16, v98
	v_or_b32_e32 v2, 0x640, v18
	v_lshl_add_u64 v[18:19], s[10:11], 0, v[2:3]
	s_nop 0
	v_mul_f32_e32 v19, 0xbfb8aa3b, v20
	v_exp_f32_e32 v19, v19
	v_lshlrev_b32_e32 v18, 16, v99
	v_add_f32_e32 v19, 1.0, v19
	v_div_scale_f32 v34, s[6:7], v19, v19, v20
	v_rcp_f32_e32 v35, v34
	s_nop 0
	v_fma_f32 v36, -v34, v35, 1.0
	v_fmac_f32_e32 v35, v36, v35
	v_div_scale_f32 v36, vcc, v20, v19, v20
	v_mul_f32_e32 v37, v36, v35
	v_fma_f32 v41, -v34, v37, v36
	v_fmac_f32_e32 v37, v41, v35
	v_fma_f32 v34, -v34, v37, v36
	v_div_fmas_f32 v34, v34, v35, v37
	v_div_fixup_f32 v19, v34, v19, v20
	v_mul_f32_e32 v20, 0xbfb8aa3b, v18
	v_exp_f32_e32 v20, v20
	v_mul_f32_e32 v16, v16, v19
	v_mul_f32_e32 v16, v17, v16
	v_mul_f32_e32 v16, v39, v16
	v_add_f32_e32 v20, 1.0, v20
	v_div_scale_f32 v34, s[6:7], v20, v20, v18
	v_rcp_f32_e32 v35, v34
	v_cvt_pk_bf16_f32 v16, v16, s0
	global_store_short v[0:1], v16, off
	v_fma_f32 v36, -v34, v35, 1.0
	v_fmac_f32_e32 v35, v36, v35
	v_div_scale_f32 v36, vcc, v18, v20, v18
	v_mul_f32_e32 v37, v36, v35
	v_fma_f32 v41, -v34, v37, v36
	v_fmac_f32_e32 v37, v41, v35
	v_fma_f32 v34, -v34, v37, v36
	v_div_fmas_f32 v34, v34, v35, v37
	v_div_fixup_f32 v18, v34, v20, v18
	v_mul_f32_e32 v0, v4, v18
	v_mul_f32_e32 v0, v17, v0
	v_mul_f32_e32 v0, v38, v0
	v_cvt_pk_bf16_f32 v4, v0, s0
	v_lshl_add_u64 v[0:1], s[12:13], 0, v[2:3]
	global_store_short v[0:1], v4, off
	v_add_f32_e32 v0, v5, v21
	s_nop 1
	v_add_f32_dpp v0, v0, v0 row_ror:8 row_mask:0xf bank_mask:0xf bound_ctrl:1
	s_nop 1
	v_add_f32_dpp v0, v0, v0 row_ror:4 row_mask:0xf bank_mask:0xf bound_ctrl:1
	s_nop 1
	v_add_f32_dpp v0, v0, v0 row_ror:2 row_mask:0xf bank_mask:0xf bound_ctrl:1
	s_nop 1
	v_add_f32_dpp v0, v0, v0 row_ror:1 row_mask:0xf bank_mask:0xf bound_ctrl:1
	v_mov_b32_e32 v1, v0
	s_nop 1
	v_permlane16_swap_b32_e32 v0, v1
	v_add_f32_e32 v0, v0, v1
	v_fmamk_f32 v4, v0, 0xbc800000, v21
	v_fmamk_f32 v5, v0, 0xbc800000, v5
	v_mul_f32_e32 v0, v4, v4
	v_fmac_f32_e32 v0, v5, v5
	s_nop 1
	v_add_f32_dpp v0, v0, v0 row_ror:8 row_mask:0xf bank_mask:0xf bound_ctrl:1
	s_nop 1
	v_add_f32_dpp v0, v0, v0 row_ror:4 row_mask:0xf bank_mask:0xf bound_ctrl:1
	s_nop 1
; __device__ __forceinline__ unsigned pk2(float lo, float hi) { return pg8::pk_bf16_rne(lo, hi); }
; __device__ __forceinline__ float bf2f(unsigned short u) { return __uint_as_float(((unsigned)u) << 16); }
; __device__ __forceinline__ float half_sum(float v) { v = row16_allsum(v); v = rows_pair_sum(v); return v; }
; __device__ __forceinline__ int crow(int r, int hi) { return (r & 3) + 8 * (r >> 2) + 4 * hi; }
; __device__ __forceinline__ void ret_out(const Params& P, int l, unsigned char* lds, int u, int tid) {
;     ...
;     for (int r = 0; r < 16; ++r) {
;         const float mean = half_sum(o0[r] + o1[r]) * (1.0f / 64.0f);
;         const float d0 = o0[r] - mean, d1 = o1[r] - mean;
;         const float var = half_sum(d0 * d0 + d1 * d1) * (1.0f / 64.0f);
;         const float rstd = 1.0f / sqrtf(var + 1e-5f);
;         const size_t t = tc + c0f + crow(r, hi);
;         const float ga = bf2f(ZR[t * 1024 + 768 + h * 64 + r32]), gb = bf2f(ZR[t * 1024 + 768 + h * 64 + 32 + r32]);
;         const float sa = ga / (1.0f + __expf(-ga)), sb = gb / (1.0f + __expf(-gb));
;         MIX[t * 1024 + 768 + h * 64 + r32] = (bf16_t)(pk2(sa * d0 * rstd * g0, 0.f) & 0xffffu);
;         MIX[t * 1024 + 768 + h * 64 + 32 + r32] = (bf16_t)(pk2(sb * d1 * rstd * g1, 0.f) & 0xffffu);
	v_add_f32_dpp v0, v0, v0 row_ror:2 row_mask:0xf bank_mask:0xf bound_ctrl:1
	s_nop 1
	v_add_f32_dpp v0, v0, v0 row_ror:1 row_mask:0xf bank_mask:0xf bound_ctrl:1
	v_mov_b32_e32 v1, v0
	s_nop 1
	v_permlane16_swap_b32_e32 v0, v1
	v_add_f32_e32 v0, v0, v1
	v_fmamk_f32 v0, v0, 0x3c800000, v200
	v_cmp_gt_f32_e32 vcc, s43, v0
	v_mul_f32_e32 v1, 0x4f800000, v0
	s_nop 0
	v_cndmask_b32_e32 v0, v0, v1, vcc
	v_sqrt_f32_e32 v1, v0
	s_nop 0
	v_add_u32_e32 v2, -1, v1
	v_fma_f32 v3, -v2, v1, v0
	v_cmp_ge_f32_e64 s[6:7], 0, v3
	v_add_u32_e32 v3, 1, v1
	s_nop 0
	v_cndmask_b32_e64 v2, v1, v2, s[6:7]
	v_fma_f32 v1, -v3, v1, v0
	v_cmp_lt_f32_e64 s[6:7], 0, v1
	s_nop 1
	v_cndmask_b32_e64 v1, v2, v3, s[6:7]
	v_mul_f32_e32 v2, 0x37800000, v1
	v_cndmask_b32_e32 v1, v1, v2, vcc
	v_cmp_class_f32_e32 vcc, v0, v175
	s_nop 1
	v_cndmask_b32_e32 v0, v1, v0, vcc
	v_div_scale_f32 v1, s[6:7], v0, v0, 1.0
	v_rcp_f32_e32 v2, v1
	s_nop 0
	v_fma_f32 v3, -v1, v2, 1.0
	v_fmac_f32_e32 v2, v3, v2
	v_div_scale_f32 v3, vcc, 1.0, v0, 1.0
	v_mul_f32_e32 v16, v3, v2
	v_fma_f32 v17, -v1, v16, v3
	v_fmac_f32_e32 v16, v17, v2
	v_fma_f32 v1, -v1, v16, v3
	v_div_fmas_f32 v1, v1, v2, v16
	v_div_fixup_f32 v16, v1, v0, 1.0
	v_or_b32_e32 v0, 9, v152
	v_mov_b32_e32 v1, v153
	v_lshl_add_u64 v[0:1], v[32:33], 0, v[0:1]
	v_lshlrev_b64 v[0:1], 11, v[0:1]
	v_or_b32_e32 v17, v0, v40
	v_or_b32_e32 v0, 0x600, v17
	v_lshl_add_u64 v[2:3], s[10:11], 0, v[0:1]
	s_nop 0
	v_mov_b32_e32 v3, v1
	v_lshl_add_u64 v[0:1], s[12:13], 0, v[0:1]
	v_lshlrev_b32_e32 v20, 16, v100
	v_or_b32_e32 v2, 0x640, v17
	v_lshl_add_u64 v[18:19], s[10:11], 0, v[2:3]
	s_nop 0
	v_mul_f32_e32 v18, 0xbfb8aa3b, v20
	v_exp_f32_e32 v18, v18
	v_lshlrev_b32_e32 v17, 16, v101
	v_add_f32_e32 v18, 1.0, v18
	v_div_scale_f32 v19, s[6:7], v18, v18, v20
	v_rcp_f32_e32 v21, v19
	s_nop 0
	v_fma_f32 v34, -v19, v21, 1.0
	v_fmac_f32_e32 v21, v34, v21
	v_div_scale_f32 v34, vcc, v20, v18, v20
	v_mul_f32_e32 v35, v34, v21
	v_fma_f32 v36, -v19, v35, v34
	v_fmac_f32_e32 v35, v36, v21
	v_fma_f32 v19, -v19, v35, v34
	v_div_fmas_f32 v19, v19, v21, v35
	v_div_fixup_f32 v18, v19, v18, v20
	v_mul_f32_e32 v19, 0xbfb8aa3b, v17
	v_exp_f32_e32 v19, v19
	v_mul_f32_e32 v5, v5, v18
	v_mul_f32_e32 v5, v16, v5
	v_mul_f32_e32 v5, v39, v5
	v_add_f32_e32 v19, 1.0, v19
	v_div_scale_f32 v20, s[6:7], v19, v19, v17
	v_rcp_f32_e32 v21, v20
	v_cvt_pk_bf16_f32 v5, v5, s0
	global_store_short v[0:1], v5, off
	v_fma_f32 v34, -v20, v21, 1.0
	v_fmac_f32_e32 v21, v34, v21
	v_div_scale_f32 v34, vcc, v17, v19, v17
	v_mul_f32_e32 v35, v34, v21
	v_fma_f32 v36, -v20, v35, v34
	v_fmac_f32_e32 v35, v36, v21
	v_fma_f32 v20, -v20, v35, v34
	v_div_fmas_f32 v20, v20, v21, v35
	v_div_fixup_f32 v17, v20, v19, v17
	v_mul_f32_e32 v0, v4, v17
	v_mul_f32_e32 v0, v16, v0
	v_mul_f32_e32 v0, v38, v0
	v_cvt_pk_bf16_f32 v4, v0, s0
	v_lshl_add_u64 v[0:1], s[12:13], 0, v[2:3]
	global_store_short v[0:1], v4, off
	v_add_f32_e32 v0, v6, v22
	s_nop 1
	v_add_f32_dpp v0, v0, v0 row_ror:8 row_mask:0xf bank_mask:0xf bound_ctrl:1
	s_nop 1
	v_add_f32_dpp v0, v0, v0 row_ror:4 row_mask:0xf bank_mask:0xf bound_ctrl:1
	s_nop 1
	v_add_f32_dpp v0, v0, v0 row_ror:2 row_mask:0xf bank_mask:0xf bound_ctrl:1
	s_nop 1
	v_add_f32_dpp v0, v0, v0 row_ror:1 row_mask:0xf bank_mask:0xf bound_ctrl:1
	v_mov_b32_e32 v1, v0
	s_nop 1
	v_permlane16_swap_b32_e32 v0, v1
	v_add_f32_e32 v0, v0, v1
	v_fmamk_f32 v4, v0, 0xbc800000, v22
	v_fmamk_f32 v5, v0, 0xbc800000, v6
	v_mul_f32_e32 v0, v4, v4
	v_fmac_f32_e32 v0, v5, v5
	s_nop 1
	v_add_f32_dpp v0, v0, v0 row_ror:8 row_mask:0xf bank_mask:0xf bound_ctrl:1
	s_nop 1
	v_add_f32_dpp v0, v0, v0 row_ror:4 row_mask:0xf bank_mask:0xf bound_ctrl:1
	s_nop 1
	v_add_f32_dpp v0, v0, v0 row_ror:2 row_mask:0xf bank_mask:0xf bound_ctrl:1
	s_nop 1
	v_add_f32_dpp v0, v0, v0 row_ror:1 row_mask:0xf bank_mask:0xf bound_ctrl:1
	v_mov_b32_e32 v1, v0
	s_nop 1
	v_permlane16_swap_b32_e32 v0, v1
	v_add_f32_e32 v0, v0, v1
	v_fmamk_f32 v0, v0, 0x3c800000, v200
	v_cmp_gt_f32_e32 vcc, s43, v0
	v_mul_f32_e32 v1, 0x4f800000, v0
	s_nop 0
	v_cndmask_b32_e32 v0, v0, v1, vcc
	v_sqrt_f32_e32 v1, v0
	s_nop 0
	v_add_u32_e32 v2, -1, v1
	v_fma_f32 v3, -v2, v1, v0
	v_cmp_ge_f32_e64 s[6:7], 0, v3
	v_add_u32_e32 v3, 1, v1
	s_nop 0
	v_cndmask_b32_e64 v2, v1, v2, s[6:7]
	v_fma_f32 v1, -v3, v1, v0
	v_cmp_lt_f32_e64 s[6:7], 0, v1
	s_nop 1
	v_cndmask_b32_e64 v1, v2, v3, s[6:7]
	v_mul_f32_e32 v2, 0x37800000, v1
	v_cndmask_b32_e32 v1, v1, v2, vcc
	v_cmp_class_f32_e32 vcc, v0, v175
	s_nop 1
	v_cndmask_b32_e32 v0, v1, v0, vcc
	v_div_scale_f32 v1, s[6:7], v0, v0, 1.0
	v_rcp_f32_e32 v2, v1
	s_nop 0
	v_fma_f32 v3, -v1, v2, 1.0
	v_fmac_f32_e32 v2, v3, v2
	v_div_scale_f32 v3, vcc, 1.0, v0, 1.0
	v_mul_f32_e32 v6, v3, v2
	v_fma_f32 v16, -v1, v6, v3
	v_fmac_f32_e32 v6, v16, v2
	v_fma_f32 v1, -v1, v6, v3
	v_div_fmas_f32 v1, v1, v2, v6
	v_div_fixup_f32 v6, v1, v0, 1.0
	v_or_b32_e32 v0, 10, v152
	v_mov_b32_e32 v1, v153
	v_lshl_add_u64 v[0:1], v[32:33], 0, v[0:1]
	v_lshlrev_b64 v[0:1], 11, v[0:1]
	v_or_b32_e32 v16, v0, v40
	v_or_b32_e32 v0, 0x600, v16
	v_lshl_add_u64 v[2:3], s[10:11], 0, v[0:1]
	s_nop 0
	v_mov_b32_e32 v3, v1
	v_lshl_add_u64 v[0:1], s[12:13], 0, v[0:1]
	v_lshlrev_b32_e32 v18, 16, v102
	v_or_b32_e32 v2, 0x640, v16
	v_lshl_add_u64 v[16:17], s[10:11], 0, v[2:3]
	s_nop 0
	v_mul_f32_e32 v17, 0xbfb8aa3b, v18
	v_exp_f32_e32 v17, v17
	v_lshlrev_b32_e32 v16, 16, v103
	v_add_f32_e32 v17, 1.0, v17
	v_div_scale_f32 v19, s[6:7], v17, v17, v18
	v_rcp_f32_e32 v20, v19
	s_nop 0
	v_fma_f32 v21, -v19, v20, 1.0
	v_fmac_f32_e32 v20, v21, v20
	v_div_scale_f32 v21, vcc, v18, v17, v18
	v_mul_f32_e32 v22, v21, v20
	v_fma_f32 v34, -v19, v22, v21
	v_fmac_f32_e32 v22, v34, v20
; __device__ __forceinline__ unsigned pk2(float lo, float hi) { return pg8::pk_bf16_rne(lo, hi); }
; __device__ __forceinline__ float bf2f(unsigned short u) { return __uint_as_float(((unsigned)u) << 16); }
; __device__ __forceinline__ float half_sum(float v) { v = row16_allsum(v); v = rows_pair_sum(v); return v; }
; __device__ __forceinline__ int crow(int r, int hi) { return (r & 3) + 8 * (r >> 2) + 4 * hi; }
; __device__ __forceinline__ void ret_out(const Params& P, int l, unsigned char* lds, int u, int tid) {
;     ...
;     for (int r = 0; r < 16; ++r) {
;         const float mean = half_sum(o0[r] + o1[r]) * (1.0f / 64.0f);
;         const float d0 = o0[r] - mean, d1 = o1[r] - mean;
;         const float var = half_sum(d0 * d0 + d1 * d1) * (1.0f / 64.0f);
;         const float rstd = 1.0f / sqrtf(var + 1e-5f);
;         const size_t t = tc + c0f + crow(r, hi);
;         const float ga = bf2f(ZR[t * 1024 + 768 + h * 64 + r32]), gb = bf2f(ZR[t * 1024 + 768 + h * 64 + 32 + r32]);
;         const float sa = ga / (1.0f + __expf(-ga)), sb = gb / (1.0f + __expf(-gb));
;         MIX[t * 1024 + 768 + h * 64 + r32] = (bf16_t)(pk2(sa * d0 * rstd * g0, 0.f) & 0xffffu);
;         MIX[t * 1024 + 768 + h * 64 + 32 + r32] = (bf16_t)(pk2(sb * d1 * rstd * g1, 0.f) & 0xffffu);
	v_fma_f32 v19, -v19, v22, v21
	v_div_fmas_f32 v19, v19, v20, v22
	v_div_fixup_f32 v17, v19, v17, v18
	v_mul_f32_e32 v18, 0xbfb8aa3b, v16
	v_exp_f32_e32 v18, v18
	v_mul_f32_e32 v5, v5, v17
	v_mul_f32_e32 v5, v6, v5
	v_mul_f32_e32 v5, v39, v5
	v_add_f32_e32 v18, 1.0, v18
	v_div_scale_f32 v19, s[6:7], v18, v18, v16
	v_rcp_f32_e32 v20, v19
	v_cvt_pk_bf16_f32 v5, v5, s0
	global_store_short v[0:1], v5, off
	v_fma_f32 v21, -v19, v20, 1.0
	v_fmac_f32_e32 v20, v21, v20
	v_div_scale_f32 v21, vcc, v16, v18, v16
	v_mul_f32_e32 v22, v21, v20
	v_fma_f32 v34, -v19, v22, v21
	v_fmac_f32_e32 v22, v34, v20
	v_fma_f32 v19, -v19, v22, v21
	v_div_fmas_f32 v19, v19, v20, v22
	v_div_fixup_f32 v16, v19, v18, v16
	v_mul_f32_e32 v0, v4, v16
	v_mul_f32_e32 v0, v6, v0
	v_mul_f32_e32 v0, v38, v0
	v_cvt_pk_bf16_f32 v4, v0, s0
	v_lshl_add_u64 v[0:1], s[12:13], 0, v[2:3]
	global_store_short v[0:1], v4, off
	v_add_f32_e32 v0, v7, v23
	s_nop 1
	v_add_f32_dpp v0, v0, v0 row_ror:8 row_mask:0xf bank_mask:0xf bound_ctrl:1
	s_nop 1
	v_add_f32_dpp v0, v0, v0 row_ror:4 row_mask:0xf bank_mask:0xf bound_ctrl:1
	s_nop 1
	v_add_f32_dpp v0, v0, v0 row_ror:2 row_mask:0xf bank_mask:0xf bound_ctrl:1
	s_nop 1
	v_add_f32_dpp v0, v0, v0 row_ror:1 row_mask:0xf bank_mask:0xf bound_ctrl:1
	v_mov_b32_e32 v1, v0
	s_nop 1
	v_permlane16_swap_b32_e32 v0, v1
	v_add_f32_e32 v0, v0, v1
	v_fmamk_f32 v4, v0, 0xbc800000, v23
	v_fmamk_f32 v5, v0, 0xbc800000, v7
	v_mul_f32_e32 v0, v4, v4
	v_fmac_f32_e32 v0, v5, v5
	s_nop 1
	v_add_f32_dpp v0, v0, v0 row_ror:8 row_mask:0xf bank_mask:0xf bound_ctrl:1
	s_nop 1
	v_add_f32_dpp v0, v0, v0 row_ror:4 row_mask:0xf bank_mask:0xf bound_ctrl:1
	s_nop 1
	v_add_f32_dpp v0, v0, v0 row_ror:2 row_mask:0xf bank_mask:0xf bound_ctrl:1
	s_nop 1
	v_add_f32_dpp v0, v0, v0 row_ror:1 row_mask:0xf bank_mask:0xf bound_ctrl:1
	v_mov_b32_e32 v1, v0
	s_nop 1
	v_permlane16_swap_b32_e32 v0, v1
	v_add_f32_e32 v0, v0, v1
	v_fmamk_f32 v0, v0, 0x3c800000, v200
	v_cmp_gt_f32_e32 vcc, s43, v0
	v_mul_f32_e32 v1, 0x4f800000, v0
	s_nop 0
	v_cndmask_b32_e32 v0, v0, v1, vcc
	v_sqrt_f32_e32 v1, v0
	s_nop 0
	v_add_u32_e32 v2, -1, v1
	v_fma_f32 v3, -v2, v1, v0
	v_cmp_ge_f32_e64 s[6:7], 0, v3
	v_add_u32_e32 v3, 1, v1
	s_nop 0
	v_cndmask_b32_e64 v2, v1, v2, s[6:7]
	v_fma_f32 v1, -v3, v1, v0
	v_cmp_lt_f32_e64 s[6:7], 0, v1
	s_nop 1
	v_cndmask_b32_e64 v1, v2, v3, s[6:7]
	v_mul_f32_e32 v2, 0x37800000, v1
	v_cndmask_b32_e32 v1, v1, v2, vcc
	v_cmp_class_f32_e32 vcc, v0, v175
	s_nop 1
	v_cndmask_b32_e32 v0, v1, v0, vcc
	v_div_scale_f32 v1, s[6:7], v0, v0, 1.0
	v_rcp_f32_e32 v2, v1
	s_nop 0
	v_fma_f32 v3, -v1, v2, 1.0
	v_fmac_f32_e32 v2, v3, v2
	v_div_scale_f32 v3, vcc, 1.0, v0, 1.0
	v_mul_f32_e32 v6, v3, v2
	v_fma_f32 v7, -v1, v6, v3
	v_fmac_f32_e32 v6, v7, v2
	v_fma_f32 v1, -v1, v6, v3
	v_div_fmas_f32 v1, v1, v2, v6
	v_div_fixup_f32 v6, v1, v0, 1.0
	v_or_b32_e32 v0, 11, v152
	v_mov_b32_e32 v1, v153
	v_lshl_add_u64 v[0:1], v[32:33], 0, v[0:1]
	v_lshlrev_b64 v[0:1], 11, v[0:1]
	v_or_b32_e32 v7, v0, v40
	v_or_b32_e32 v0, 0x600, v7
	v_lshl_add_u64 v[2:3], s[10:11], 0, v[0:1]
	s_nop 0
	v_mov_b32_e32 v3, v1
	v_lshl_add_u64 v[0:1], s[12:13], 0, v[0:1]
	v_lshlrev_b32_e32 v18, 16, v104
	v_or_b32_e32 v2, 0x640, v7
	v_lshl_add_u64 v[16:17], s[10:11], 0, v[2:3]
	s_nop 0
	v_mul_f32_e32 v16, 0xbfb8aa3b, v18
	v_exp_f32_e32 v16, v16
	v_lshlrev_b32_e32 v7, 16, v105
	v_add_f32_e32 v16, 1.0, v16
	v_div_scale_f32 v17, s[6:7], v16, v16, v18
	v_rcp_f32_e32 v19, v17
	s_nop 0
	v_fma_f32 v20, -v17, v19, 1.0
	v_fmac_f32_e32 v19, v20, v19
	v_div_scale_f32 v20, vcc, v18, v16, v18
	v_mul_f32_e32 v21, v20, v19
	v_fma_f32 v22, -v17, v21, v20
	v_fmac_f32_e32 v21, v22, v19
	v_fma_f32 v17, -v17, v21, v20
	v_div_fmas_f32 v17, v17, v19, v21
	v_div_fixup_f32 v16, v17, v16, v18
	v_mul_f32_e32 v17, 0xbfb8aa3b, v7
	v_exp_f32_e32 v17, v17
	v_mul_f32_e32 v5, v5, v16
	v_mul_f32_e32 v5, v6, v5
	v_mul_f32_e32 v5, v39, v5
	v_add_f32_e32 v17, 1.0, v17
	v_div_scale_f32 v18, s[6:7], v17, v17, v7
	v_rcp_f32_e32 v19, v18
	v_cvt_pk_bf16_f32 v5, v5, s0
	global_store_short v[0:1], v5, off
	v_fma_f32 v20, -v18, v19, 1.0
	v_fmac_f32_e32 v19, v20, v19
	v_div_scale_f32 v20, vcc, v7, v17, v7
	v_mul_f32_e32 v21, v20, v19
	v_fma_f32 v22, -v18, v21, v20
	v_fmac_f32_e32 v21, v22, v19
	v_fma_f32 v18, -v18, v21, v20
	v_div_fmas_f32 v18, v18, v19, v21
	v_div_fixup_f32 v7, v18, v17, v7
	v_mul_f32_e32 v0, v4, v7
	v_mul_f32_e32 v0, v6, v0
	v_mul_f32_e32 v0, v38, v0
	v_cvt_pk_bf16_f32 v4, v0, s0
	v_lshl_add_u64 v[0:1], s[12:13], 0, v[2:3]
	global_store_short v[0:1], v4, off
	v_add_f32_e32 v0, v8, v24
	s_nop 1
	v_add_f32_dpp v0, v0, v0 row_ror:8 row_mask:0xf bank_mask:0xf bound_ctrl:1
	s_nop 1
	v_add_f32_dpp v0, v0, v0 row_ror:4 row_mask:0xf bank_mask:0xf bound_ctrl:1
	s_nop 1
	v_add_f32_dpp v0, v0, v0 row_ror:2 row_mask:0xf bank_mask:0xf bound_ctrl:1
	s_nop 1
	v_add_f32_dpp v0, v0, v0 row_ror:1 row_mask:0xf bank_mask:0xf bound_ctrl:1
	v_mov_b32_e32 v1, v0
	s_nop 1
	v_permlane16_swap_b32_e32 v0, v1
	v_add_f32_e32 v0, v0, v1
	v_fmamk_f32 v4, v0, 0xbc800000, v24
	v_fmamk_f32 v5, v0, 0xbc800000, v8
	v_mul_f32_e32 v0, v4, v4
	v_fmac_f32_e32 v0, v5, v5
	s_nop 1
	v_add_f32_dpp v0, v0, v0 row_ror:8 row_mask:0xf bank_mask:0xf bound_ctrl:1
	s_nop 1
	v_add_f32_dpp v0, v0, v0 row_ror:4 row_mask:0xf bank_mask:0xf bound_ctrl:1
	s_nop 1
	v_add_f32_dpp v0, v0, v0 row_ror:2 row_mask:0xf bank_mask:0xf bound_ctrl:1
	s_nop 1
	v_add_f32_dpp v0, v0, v0 row_ror:1 row_mask:0xf bank_mask:0xf bound_ctrl:1
	v_mov_b32_e32 v1, v0
	s_nop 1
	v_permlane16_swap_b32_e32 v0, v1
	v_add_f32_e32 v0, v0, v1
	v_fmamk_f32 v0, v0, 0x3c800000, v200
	v_cmp_gt_f32_e32 vcc, s43, v0
	v_mul_f32_e32 v1, 0x4f800000, v0
; __device__ __forceinline__ unsigned pk2(float lo, float hi) { return pg8::pk_bf16_rne(lo, hi); }
; __device__ __forceinline__ float bf2f(unsigned short u) { return __uint_as_float(((unsigned)u) << 16); }
; __device__ __forceinline__ float half_sum(float v) { v = row16_allsum(v); v = rows_pair_sum(v); return v; }
; __device__ __forceinline__ int crow(int r, int hi) { return (r & 3) + 8 * (r >> 2) + 4 * hi; }
; __device__ __forceinline__ void ret_out(const Params& P, int l, unsigned char* lds, int u, int tid) {
;     ...
;     for (int r = 0; r < 16; ++r) {
;         const float mean = half_sum(o0[r] + o1[r]) * (1.0f / 64.0f);
;         const float d0 = o0[r] - mean, d1 = o1[r] - mean;
;         const float var = half_sum(d0 * d0 + d1 * d1) * (1.0f / 64.0f);
;         const float rstd = 1.0f / sqrtf(var + 1e-5f);
;         const size_t t = tc + c0f + crow(r, hi);
;         const float ga = bf2f(ZR[t * 1024 + 768 + h * 64 + r32]), gb = bf2f(ZR[t * 1024 + 768 + h * 64 + 32 + r32]);
;         const float sa = ga / (1.0f + __expf(-ga)), sb = gb / (1.0f + __expf(-gb));
;         MIX[t * 1024 + 768 + h * 64 + r32] = (bf16_t)(pk2(sa * d0 * rstd * g0, 0.f) & 0xffffu);
;         MIX[t * 1024 + 768 + h * 64 + 32 + r32] = (bf16_t)(pk2(sb * d1 * rstd * g1, 0.f) & 0xffffu);
	s_nop 0
	v_cndmask_b32_e32 v0, v0, v1, vcc
	v_sqrt_f32_e32 v1, v0
	s_nop 0
	v_add_u32_e32 v2, -1, v1
	v_fma_f32 v3, -v2, v1, v0
	v_cmp_ge_f32_e64 s[6:7], 0, v3
	v_add_u32_e32 v3, 1, v1
	s_nop 0
	v_cndmask_b32_e64 v2, v1, v2, s[6:7]
	v_fma_f32 v1, -v3, v1, v0
	v_cmp_lt_f32_e64 s[6:7], 0, v1
	s_nop 1
	v_cndmask_b32_e64 v1, v2, v3, s[6:7]
	v_mul_f32_e32 v2, 0x37800000, v1
	v_cndmask_b32_e32 v1, v1, v2, vcc
	v_cmp_class_f32_e32 vcc, v0, v175
	s_nop 1
	v_cndmask_b32_e32 v0, v1, v0, vcc
	v_div_scale_f32 v1, s[6:7], v0, v0, 1.0
	v_rcp_f32_e32 v2, v1
	s_nop 0
	v_fma_f32 v3, -v1, v2, 1.0
	v_fmac_f32_e32 v2, v3, v2
	v_div_scale_f32 v3, vcc, 1.0, v0, 1.0
	v_mul_f32_e32 v6, v3, v2
	v_fma_f32 v7, -v1, v6, v3
	v_fmac_f32_e32 v6, v7, v2
	v_fma_f32 v1, -v1, v6, v3
	v_div_fmas_f32 v1, v1, v2, v6
	v_div_fixup_f32 v6, v1, v0, 1.0
	v_or_b32_e32 v0, 16, v152
	v_mov_b32_e32 v1, v153
	v_lshl_add_u64 v[0:1], v[32:33], 0, v[0:1]
	v_lshlrev_b64 v[0:1], 11, v[0:1]
	v_or_b32_e32 v7, v0, v40
	v_or_b32_e32 v0, 0x600, v7
	v_lshl_add_u64 v[2:3], s[10:11], 0, v[0:1]
	s_nop 0
	v_mov_b32_e32 v3, v1
	v_lshl_add_u64 v[0:1], s[12:13], 0, v[0:1]
	v_lshlrev_b32_e32 v8, 16, v106
	v_or_b32_e32 v2, 0x640, v7
	v_lshl_add_u64 v[16:17], s[10:11], 0, v[2:3]
	s_nop 0
	v_mul_f32_e32 v16, 0xbfb8aa3b, v8
	v_exp_f32_e32 v16, v16
	v_lshlrev_b32_e32 v7, 16, v107
	v_add_f32_e32 v16, 1.0, v16
	v_div_scale_f32 v17, s[6:7], v16, v16, v8
	v_rcp_f32_e32 v18, v17
	s_nop 0
	v_fma_f32 v19, -v17, v18, 1.0
	v_fmac_f32_e32 v18, v19, v18
	v_div_scale_f32 v19, vcc, v8, v16, v8
	v_mul_f32_e32 v20, v19, v18
	v_fma_f32 v21, -v17, v20, v19
	v_fmac_f32_e32 v20, v21, v18
	v_fma_f32 v17, -v17, v20, v19
	v_div_fmas_f32 v17, v17, v18, v20
	v_div_fixup_f32 v8, v17, v16, v8
	v_mul_f32_e32 v16, 0xbfb8aa3b, v7
	v_exp_f32_e32 v16, v16
	v_mul_f32_e32 v5, v5, v8
	v_mul_f32_e32 v5, v6, v5
	v_mul_f32_e32 v5, v39, v5
	v_add_f32_e32 v16, 1.0, v16
	v_div_scale_f32 v17, s[6:7], v16, v16, v7
	v_rcp_f32_e32 v18, v17
	v_cvt_pk_bf16_f32 v5, v5, s0
	global_store_short v[0:1], v5, off
	v_fma_f32 v19, -v17, v18, 1.0
	v_fmac_f32_e32 v18, v19, v18
	v_div_scale_f32 v19, vcc, v7, v16, v7
	v_mul_f32_e32 v20, v19, v18
	v_fma_f32 v21, -v17, v20, v19
	v_fmac_f32_e32 v20, v21, v18
	v_fma_f32 v17, -v17, v20, v19
	v_div_fmas_f32 v17, v17, v18, v20
	v_div_fixup_f32 v7, v17, v16, v7
	v_mul_f32_e32 v0, v4, v7
	v_mul_f32_e32 v0, v6, v0
	v_mul_f32_e32 v0, v38, v0
	v_cvt_pk_bf16_f32 v4, v0, s0
	v_lshl_add_u64 v[0:1], s[12:13], 0, v[2:3]
	global_store_short v[0:1], v4, off
	v_add_f32_e32 v0, v9, v25
	s_nop 1
	v_add_f32_dpp v0, v0, v0 row_ror:8 row_mask:0xf bank_mask:0xf bound_ctrl:1
	s_nop 1
	v_add_f32_dpp v0, v0, v0 row_ror:4 row_mask:0xf bank_mask:0xf bound_ctrl:1
	s_nop 1
	v_add_f32_dpp v0, v0, v0 row_ror:2 row_mask:0xf bank_mask:0xf bound_ctrl:1
	s_nop 1
	v_add_f32_dpp v0, v0, v0 row_ror:1 row_mask:0xf bank_mask:0xf bound_ctrl:1
	v_mov_b32_e32 v1, v0
	s_nop 1
	v_permlane16_swap_b32_e32 v0, v1
	v_add_f32_e32 v0, v0, v1
	v_fmamk_f32 v4, v0, 0xbc800000, v25
	v_fmamk_f32 v5, v0, 0xbc800000, v9
	v_mul_f32_e32 v0, v4, v4
	v_fmac_f32_e32 v0, v5, v5
	s_nop 1
	v_add_f32_dpp v0, v0, v0 row_ror:8 row_mask:0xf bank_mask:0xf bound_ctrl:1
	s_nop 1
	v_add_f32_dpp v0, v0, v0 row_ror:4 row_mask:0xf bank_mask:0xf bound_ctrl:1
	s_nop 1
	v_add_f32_dpp v0, v0, v0 row_ror:2 row_mask:0xf bank_mask:0xf bound_ctrl:1
	s_nop 1
	v_add_f32_dpp v0, v0, v0 row_ror:1 row_mask:0xf bank_mask:0xf bound_ctrl:1
	v_mov_b32_e32 v1, v0
	s_nop 1
	v_permlane16_swap_b32_e32 v0, v1
	v_add_f32_e32 v0, v0, v1
	v_fmamk_f32 v0, v0, 0x3c800000, v200
	v_cmp_gt_f32_e32 vcc, s43, v0
	v_mul_f32_e32 v1, 0x4f800000, v0
	s_nop 0
	v_cndmask_b32_e32 v0, v0, v1, vcc
	v_sqrt_f32_e32 v1, v0
	s_nop 0
	v_add_u32_e32 v2, -1, v1
	v_fma_f32 v3, -v2, v1, v0
	v_cmp_ge_f32_e64 s[6:7], 0, v3
	v_add_u32_e32 v3, 1, v1
	s_nop 0
	v_cndmask_b32_e64 v2, v1, v2, s[6:7]
	v_fma_f32 v1, -v3, v1, v0
	v_cmp_lt_f32_e64 s[6:7], 0, v1
	s_nop 1
	v_cndmask_b32_e64 v1, v2, v3, s[6:7]
	v_mul_f32_e32 v2, 0x37800000, v1
	v_cndmask_b32_e32 v1, v1, v2, vcc
	v_cmp_class_f32_e32 vcc, v0, v175
	s_nop 1
	v_cndmask_b32_e32 v0, v1, v0, vcc
	v_div_scale_f32 v1, s[6:7], v0, v0, 1.0
	v_rcp_f32_e32 v2, v1
	s_nop 0
	v_fma_f32 v3, -v1, v2, 1.0
	v_fmac_f32_e32 v2, v3, v2
	v_div_scale_f32 v3, vcc, 1.0, v0, 1.0
	v_mul_f32_e32 v6, v3, v2
	v_fma_f32 v7, -v1, v6, v3
	v_fmac_f32_e32 v6, v7, v2
	v_fma_f32 v1, -v1, v6, v3
	v_div_fmas_f32 v1, v1, v2, v6
	v_div_fixup_f32 v6, v1, v0, 1.0
	v_or_b32_e32 v0, 17, v152
	v_mov_b32_e32 v1, v153
	v_lshl_add_u64 v[0:1], v[32:33], 0, v[0:1]
	v_lshlrev_b64 v[0:1], 11, v[0:1]
	v_or_b32_e32 v7, v0, v40
	v_or_b32_e32 v0, 0x600, v7
	v_lshl_add_u64 v[2:3], s[10:11], 0, v[0:1]
	s_nop 0
	v_mov_b32_e32 v3, v1
	v_lshl_add_u64 v[0:1], s[12:13], 0, v[0:1]
	v_lshlrev_b32_e32 v16, 16, v108
	v_or_b32_e32 v2, 0x640, v7
	v_lshl_add_u64 v[8:9], s[10:11], 0, v[2:3]
	s_nop 0
	v_mul_f32_e32 v8, 0xbfb8aa3b, v16
	v_exp_f32_e32 v8, v8
	v_lshlrev_b32_e32 v7, 16, v109
	v_add_f32_e32 v8, 1.0, v8
	v_div_scale_f32 v9, s[6:7], v8, v8, v16
	v_rcp_f32_e32 v17, v9
	s_nop 0
	v_fma_f32 v18, -v9, v17, 1.0
	v_fmac_f32_e32 v17, v18, v17
	v_div_scale_f32 v18, vcc, v16, v8, v16
	v_mul_f32_e32 v19, v18, v17
	v_fma_f32 v20, -v9, v19, v18
	v_fmac_f32_e32 v19, v20, v17
	v_fma_f32 v9, -v9, v19, v18
	v_div_fmas_f32 v9, v9, v17, v19
	v_div_fixup_f32 v8, v9, v8, v16
	v_mul_f32_e32 v9, 0xbfb8aa3b, v7
	v_exp_f32_e32 v9, v9
	v_mul_f32_e32 v5, v5, v8
	v_mul_f32_e32 v5, v6, v5
	v_mul_f32_e32 v5, v39, v5
	v_add_f32_e32 v9, 1.0, v9
	v_div_scale_f32 v16, s[6:7], v9, v9, v7
	v_rcp_f32_e32 v17, v16
	v_cvt_pk_bf16_f32 v5, v5, s0
	global_store_short v[0:1], v5, off
; __device__ __forceinline__ unsigned pk2(float lo, float hi) { return pg8::pk_bf16_rne(lo, hi); }
; __device__ __forceinline__ float bf2f(unsigned short u) { return __uint_as_float(((unsigned)u) << 16); }
; __device__ __forceinline__ float half_sum(float v) { v = row16_allsum(v); v = rows_pair_sum(v); return v; }
; __device__ __forceinline__ int crow(int r, int hi) { return (r & 3) + 8 * (r >> 2) + 4 * hi; }
; __device__ __forceinline__ void ret_out(const Params& P, int l, unsigned char* lds, int u, int tid) {
;     ...
;     for (int r = 0; r < 16; ++r) {
;         const float mean = half_sum(o0[r] + o1[r]) * (1.0f / 64.0f);
;         const float d0 = o0[r] - mean, d1 = o1[r] - mean;
;         const float var = half_sum(d0 * d0 + d1 * d1) * (1.0f / 64.0f);
;         const float rstd = 1.0f / sqrtf(var + 1e-5f);
;         const size_t t = tc + c0f + crow(r, hi);
;         const float ga = bf2f(ZR[t * 1024 + 768 + h * 64 + r32]), gb = bf2f(ZR[t * 1024 + 768 + h * 64 + 32 + r32]);
;         const float sa = ga / (1.0f + __expf(-ga)), sb = gb / (1.0f + __expf(-gb));
;         MIX[t * 1024 + 768 + h * 64 + r32] = (bf16_t)(pk2(sa * d0 * rstd * g0, 0.f) & 0xffffu);
;         MIX[t * 1024 + 768 + h * 64 + 32 + r32] = (bf16_t)(pk2(sb * d1 * rstd * g1, 0.f) & 0xffffu);
;     }
	v_fma_f32 v18, -v16, v17, 1.0
	v_fmac_f32_e32 v17, v18, v17
	v_div_scale_f32 v18, vcc, v7, v9, v7
	v_mul_f32_e32 v19, v18, v17
	v_fma_f32 v20, -v16, v19, v18
	v_fmac_f32_e32 v19, v20, v17
	v_fma_f32 v16, -v16, v19, v18
	v_div_fmas_f32 v16, v16, v17, v19
	v_div_fixup_f32 v7, v16, v9, v7
	v_mul_f32_e32 v0, v4, v7
	v_mul_f32_e32 v0, v6, v0
	v_mul_f32_e32 v0, v38, v0
	v_cvt_pk_bf16_f32 v4, v0, s0
	v_lshl_add_u64 v[0:1], s[12:13], 0, v[2:3]
	global_store_short v[0:1], v4, off
	v_add_f32_e32 v0, v10, v26
	s_nop 1
	v_add_f32_dpp v0, v0, v0 row_ror:8 row_mask:0xf bank_mask:0xf bound_ctrl:1
	s_nop 1
	v_add_f32_dpp v0, v0, v0 row_ror:4 row_mask:0xf bank_mask:0xf bound_ctrl:1
	s_nop 1
	v_add_f32_dpp v0, v0, v0 row_ror:2 row_mask:0xf bank_mask:0xf bound_ctrl:1
	s_nop 1
	v_add_f32_dpp v0, v0, v0 row_ror:1 row_mask:0xf bank_mask:0xf bound_ctrl:1
	v_mov_b32_e32 v1, v0
	s_nop 1
	v_permlane16_swap_b32_e32 v0, v1
	v_add_f32_e32 v0, v0, v1
	v_fmamk_f32 v4, v0, 0xbc800000, v26
	v_fmamk_f32 v5, v0, 0xbc800000, v10
	v_mul_f32_e32 v0, v4, v4
	v_fmac_f32_e32 v0, v5, v5
	s_nop 1
	v_add_f32_dpp v0, v0, v0 row_ror:8 row_mask:0xf bank_mask:0xf bound_ctrl:1
	s_nop 1
	v_add_f32_dpp v0, v0, v0 row_ror:4 row_mask:0xf bank_mask:0xf bound_ctrl:1
	s_nop 1
	v_add_f32_dpp v0, v0, v0 row_ror:2 row_mask:0xf bank_mask:0xf bound_ctrl:1
	s_nop 1
	v_add_f32_dpp v0, v0, v0 row_ror:1 row_mask:0xf bank_mask:0xf bound_ctrl:1
	v_mov_b32_e32 v1, v0
	s_nop 1
	v_permlane16_swap_b32_e32 v0, v1
	v_add_f32_e32 v0, v0, v1
	v_fmamk_f32 v0, v0, 0x3c800000, v200
	v_cmp_gt_f32_e32 vcc, s43, v0
	v_mul_f32_e32 v1, 0x4f800000, v0
	s_nop 0
	v_cndmask_b32_e32 v0, v0, v1, vcc
	v_sqrt_f32_e32 v1, v0
	s_nop 0
	v_add_u32_e32 v2, -1, v1
	v_fma_f32 v3, -v2, v1, v0
	v_cmp_ge_f32_e64 s[6:7], 0, v3
	v_add_u32_e32 v3, 1, v1
	s_nop 0
	v_cndmask_b32_e64 v2, v1, v2, s[6:7]
	v_fma_f32 v1, -v3, v1, v0
	v_cmp_lt_f32_e64 s[6:7], 0, v1
	s_nop 1
	v_cndmask_b32_e64 v1, v2, v3, s[6:7]
	v_mul_f32_e32 v2, 0x37800000, v1
	v_cndmask_b32_e32 v1, v1, v2, vcc
	v_cmp_class_f32_e32 vcc, v0, v175
	s_nop 1
	v_cndmask_b32_e32 v0, v1, v0, vcc
	v_div_scale_f32 v1, s[6:7], v0, v0, 1.0
	v_rcp_f32_e32 v2, v1
	s_nop 0
	v_fma_f32 v3, -v1, v2, 1.0
	v_fmac_f32_e32 v2, v3, v2
	v_div_scale_f32 v3, vcc, 1.0, v0, 1.0
	v_mul_f32_e32 v6, v3, v2
	v_fma_f32 v7, -v1, v6, v3
	v_fmac_f32_e32 v6, v7, v2
	v_fma_f32 v1, -v1, v6, v3
	v_div_fmas_f32 v1, v1, v2, v6
	v_div_fixup_f32 v6, v1, v0, 1.0
	v_or_b32_e32 v0, 18, v152
	v_mov_b32_e32 v1, v153
	v_lshl_add_u64 v[0:1], v[32:33], 0, v[0:1]
	v_lshlrev_b64 v[0:1], 11, v[0:1]
	v_or_b32_e32 v7, v0, v40
	v_or_b32_e32 v0, 0x600, v7
	v_lshl_add_u64 v[2:3], s[10:11], 0, v[0:1]
	s_nop 0
	v_mov_b32_e32 v3, v1
	v_lshl_add_u64 v[0:1], s[12:13], 0, v[0:1]
	v_lshlrev_b32_e32 v10, 16, v110
	v_or_b32_e32 v2, 0x640, v7
	v_lshl_add_u64 v[8:9], s[10:11], 0, v[2:3]
	s_nop 0
	v_mul_f32_e32 v8, 0xbfb8aa3b, v10
	v_exp_f32_e32 v8, v8
	v_lshlrev_b32_e32 v7, 16, v111
	v_add_f32_e32 v8, 1.0, v8
	v_div_scale_f32 v9, s[6:7], v8, v8, v10
	v_rcp_f32_e32 v16, v9
	s_nop 0
	v_fma_f32 v17, -v9, v16, 1.0
	v_fmac_f32_e32 v16, v17, v16
	v_div_scale_f32 v17, vcc, v10, v8, v10
	v_mul_f32_e32 v18, v17, v16
	v_fma_f32 v19, -v9, v18, v17
	v_fmac_f32_e32 v18, v19, v16
	v_fma_f32 v9, -v9, v18, v17
	v_div_fmas_f32 v9, v9, v16, v18
	v_div_fixup_f32 v8, v9, v8, v10
	v_mul_f32_e32 v9, 0xbfb8aa3b, v7
	v_exp_f32_e32 v9, v9
	v_mul_f32_e32 v5, v5, v8
	v_mul_f32_e32 v5, v6, v5
	v_mul_f32_e32 v5, v39, v5
	v_add_f32_e32 v9, 1.0, v9
	v_div_scale_f32 v10, s[6:7], v9, v9, v7
	v_rcp_f32_e32 v16, v10
	v_cvt_pk_bf16_f32 v5, v5, s0
	global_store_short v[0:1], v5, off
	v_fma_f32 v17, -v10, v16, 1.0
	v_fmac_f32_e32 v16, v17, v16
	v_div_scale_f32 v17, vcc, v7, v9, v7
	v_mul_f32_e32 v18, v17, v16
	v_fma_f32 v19, -v10, v18, v17
	v_fmac_f32_e32 v18, v19, v16
	v_fma_f32 v10, -v10, v18, v17
	v_div_fmas_f32 v10, v10, v16, v18
	v_div_fixup_f32 v7, v10, v9, v7
	v_mul_f32_e32 v0, v4, v7
	v_mul_f32_e32 v0, v6, v0
	v_mul_f32_e32 v0, v38, v0
	v_cvt_pk_bf16_f32 v4, v0, s0
	v_lshl_add_u64 v[0:1], s[12:13], 0, v[2:3]
	global_store_short v[0:1], v4, off
	v_add_f32_e32 v0, v11, v27
	s_nop 1
	v_add_f32_dpp v0, v0, v0 row_ror:8 row_mask:0xf bank_mask:0xf bound_ctrl:1
	s_nop 1
	v_add_f32_dpp v0, v0, v0 row_ror:4 row_mask:0xf bank_mask:0xf bound_ctrl:1
	s_nop 1
	v_add_f32_dpp v0, v0, v0 row_ror:2 row_mask:0xf bank_mask:0xf bound_ctrl:1
	s_nop 1
	v_add_f32_dpp v0, v0, v0 row_ror:1 row_mask:0xf bank_mask:0xf bound_ctrl:1
	v_mov_b32_e32 v1, v0
	s_nop 1
	v_permlane16_swap_b32_e32 v0, v1
	v_add_f32_e32 v0, v0, v1
	v_fmamk_f32 v4, v0, 0xbc800000, v27
	v_fmamk_f32 v5, v0, 0xbc800000, v11
	v_mul_f32_e32 v0, v4, v4
	v_fmac_f32_e32 v0, v5, v5
	s_nop 1
	v_add_f32_dpp v0, v0, v0 row_ror:8 row_mask:0xf bank_mask:0xf bound_ctrl:1
	s_nop 1
	v_add_f32_dpp v0, v0, v0 row_ror:4 row_mask:0xf bank_mask:0xf bound_ctrl:1
	s_nop 1
	v_add_f32_dpp v0, v0, v0 row_ror:2 row_mask:0xf bank_mask:0xf bound_ctrl:1
	s_nop 1
	v_add_f32_dpp v0, v0, v0 row_ror:1 row_mask:0xf bank_mask:0xf bound_ctrl:1
	v_mov_b32_e32 v1, v0
	s_nop 1
	v_permlane16_swap_b32_e32 v0, v1
	v_add_f32_e32 v0, v0, v1
	v_fmamk_f32 v0, v0, 0x3c800000, v200
	v_cmp_gt_f32_e32 vcc, s43, v0
	v_mul_f32_e32 v1, 0x4f800000, v0
	s_nop 0
	v_cndmask_b32_e32 v0, v0, v1, vcc
	v_sqrt_f32_e32 v1, v0
	s_nop 0
	v_add_u32_e32 v2, -1, v1
	v_fma_f32 v3, -v2, v1, v0
	v_cmp_ge_f32_e64 s[6:7], 0, v3
	v_add_u32_e32 v3, 1, v1
	s_nop 0
	v_cndmask_b32_e64 v2, v1, v2, s[6:7]
	v_fma_f32 v1, -v3, v1, v0
	v_cmp_lt_f32_e64 s[6:7], 0, v1
	s_nop 1
	v_cndmask_b32_e64 v1, v2, v3, s[6:7]
	v_mul_f32_e32 v2, 0x37800000, v1
	v_cndmask_b32_e32 v1, v1, v2, vcc
	v_cmp_class_f32_e32 vcc, v0, v175
; __device__ __forceinline__ unsigned pk2(float lo, float hi) { return pg8::pk_bf16_rne(lo, hi); }
; __device__ __forceinline__ float bf2f(unsigned short u) { return __uint_as_float(((unsigned)u) << 16); }
; __device__ __forceinline__ float half_sum(float v) { v = row16_allsum(v); v = rows_pair_sum(v); return v; }
; __device__ __forceinline__ int crow(int r, int hi) { return (r & 3) + 8 * (r >> 2) + 4 * hi; }
; __device__ __forceinline__ void ret_out(const Params& P, int l, unsigned char* lds, int u, int tid) {
;     ...
;     for (int r = 0; r < 16; ++r) {
;         const float mean = half_sum(o0[r] + o1[r]) * (1.0f / 64.0f);
;         const float d0 = o0[r] - mean, d1 = o1[r] - mean;
;         const float var = half_sum(d0 * d0 + d1 * d1) * (1.0f / 64.0f);
;         const float rstd = 1.0f / sqrtf(var + 1e-5f);
;         const size_t t = tc + c0f + crow(r, hi);
;         const float ga = bf2f(ZR[t * 1024 + 768 + h * 64 + r32]), gb = bf2f(ZR[t * 1024 + 768 + h * 64 + 32 + r32]);
;         const float sa = ga / (1.0f + __expf(-ga)), sb = gb / (1.0f + __expf(-gb));
;         MIX[t * 1024 + 768 + h * 64 + r32] = (bf16_t)(pk2(sa * d0 * rstd * g0, 0.f) & 0xffffu);
;         MIX[t * 1024 + 768 + h * 64 + 32 + r32] = (bf16_t)(pk2(sb * d1 * rstd * g1, 0.f) & 0xffffu);
;     }
	s_nop 1
	v_cndmask_b32_e32 v0, v1, v0, vcc
	v_div_scale_f32 v1, s[6:7], v0, v0, 1.0
	v_rcp_f32_e32 v2, v1
	s_nop 0
	v_fma_f32 v3, -v1, v2, 1.0
	v_fmac_f32_e32 v2, v3, v2
	v_div_scale_f32 v3, vcc, 1.0, v0, 1.0
	v_mul_f32_e32 v6, v3, v2
	v_fma_f32 v7, -v1, v6, v3
	v_fmac_f32_e32 v6, v7, v2
	v_fma_f32 v1, -v1, v6, v3
	v_div_fmas_f32 v1, v1, v2, v6
	v_div_fixup_f32 v6, v1, v0, 1.0
	v_or_b32_e32 v0, 19, v152
	v_mov_b32_e32 v1, v153
	v_lshl_add_u64 v[0:1], v[32:33], 0, v[0:1]
	v_lshlrev_b64 v[0:1], 11, v[0:1]
	v_or_b32_e32 v7, v0, v40
	v_or_b32_e32 v0, 0x600, v7
	v_lshl_add_u64 v[2:3], s[10:11], 0, v[0:1]
	s_nop 0
	v_mov_b32_e32 v3, v1
	v_lshl_add_u64 v[0:1], s[12:13], 0, v[0:1]
	v_lshlrev_b32_e32 v10, 16, v112
	v_or_b32_e32 v2, 0x640, v7
	v_lshl_add_u64 v[8:9], s[10:11], 0, v[2:3]
	s_nop 0
	v_mul_f32_e32 v8, 0xbfb8aa3b, v10
	v_exp_f32_e32 v8, v8
	v_lshlrev_b32_e32 v7, 16, v113
	v_add_f32_e32 v8, 1.0, v8
	v_div_scale_f32 v9, s[6:7], v8, v8, v10
	v_rcp_f32_e32 v11, v9
	s_nop 0
	v_fma_f32 v16, -v9, v11, 1.0
	v_fmac_f32_e32 v11, v16, v11
	v_div_scale_f32 v16, vcc, v10, v8, v10
	v_mul_f32_e32 v17, v16, v11
	v_fma_f32 v18, -v9, v17, v16
	v_fmac_f32_e32 v17, v18, v11
	v_fma_f32 v9, -v9, v17, v16
	v_div_fmas_f32 v9, v9, v11, v17
	v_div_fixup_f32 v8, v9, v8, v10
	v_mul_f32_e32 v9, 0xbfb8aa3b, v7
	v_exp_f32_e32 v9, v9
	v_mul_f32_e32 v5, v5, v8
	v_mul_f32_e32 v5, v6, v5
	v_mul_f32_e32 v5, v39, v5
	v_add_f32_e32 v9, 1.0, v9
	v_div_scale_f32 v10, s[6:7], v9, v9, v7
	v_rcp_f32_e32 v11, v10
	v_cvt_pk_bf16_f32 v5, v5, s0
	global_store_short v[0:1], v5, off
	v_fma_f32 v16, -v10, v11, 1.0
	v_fmac_f32_e32 v11, v16, v11
	v_div_scale_f32 v16, vcc, v7, v9, v7
	v_mul_f32_e32 v17, v16, v11
	v_fma_f32 v18, -v10, v17, v16
	v_fmac_f32_e32 v17, v18, v11
	v_fma_f32 v10, -v10, v17, v16
	v_div_fmas_f32 v10, v10, v11, v17
	v_div_fixup_f32 v7, v10, v9, v7
	v_mul_f32_e32 v0, v4, v7
	v_mul_f32_e32 v0, v6, v0
	v_mul_f32_e32 v0, v38, v0
	v_cvt_pk_bf16_f32 v4, v0, s0
	v_lshl_add_u64 v[0:1], s[12:13], 0, v[2:3]
	global_store_short v[0:1], v4, off
	v_add_f32_e32 v0, v12, v28
	s_nop 1
	v_add_f32_dpp v0, v0, v0 row_ror:8 row_mask:0xf bank_mask:0xf bound_ctrl:1
	s_nop 1
	v_add_f32_dpp v0, v0, v0 row_ror:4 row_mask:0xf bank_mask:0xf bound_ctrl:1
	s_nop 1
	v_add_f32_dpp v0, v0, v0 row_ror:2 row_mask:0xf bank_mask:0xf bound_ctrl:1
	s_nop 1
	v_add_f32_dpp v0, v0, v0 row_ror:1 row_mask:0xf bank_mask:0xf bound_ctrl:1
	v_mov_b32_e32 v1, v0
	s_nop 1
	v_permlane16_swap_b32_e32 v0, v1
	v_add_f32_e32 v0, v0, v1
	v_fmamk_f32 v4, v0, 0xbc800000, v28
	v_fmamk_f32 v5, v0, 0xbc800000, v12
	v_mul_f32_e32 v0, v4, v4
	v_fmac_f32_e32 v0, v5, v5
	s_nop 1
	v_add_f32_dpp v0, v0, v0 row_ror:8 row_mask:0xf bank_mask:0xf bound_ctrl:1
	s_nop 1
	v_add_f32_dpp v0, v0, v0 row_ror:4 row_mask:0xf bank_mask:0xf bound_ctrl:1
	s_nop 1
	v_add_f32_dpp v0, v0, v0 row_ror:2 row_mask:0xf bank_mask:0xf bound_ctrl:1
	s_nop 1
	v_add_f32_dpp v0, v0, v0 row_ror:1 row_mask:0xf bank_mask:0xf bound_ctrl:1
	v_mov_b32_e32 v1, v0
	s_nop 1
	v_permlane16_swap_b32_e32 v0, v1
	v_add_f32_e32 v0, v0, v1
	v_fmamk_f32 v0, v0, 0x3c800000, v200
	v_cmp_gt_f32_e32 vcc, s43, v0
	v_mul_f32_e32 v1, 0x4f800000, v0
	s_nop 0
	v_cndmask_b32_e32 v0, v0, v1, vcc
	v_sqrt_f32_e32 v1, v0
	s_nop 0
	v_add_u32_e32 v2, -1, v1
	v_fma_f32 v3, -v2, v1, v0
	v_cmp_ge_f32_e64 s[6:7], 0, v3
	v_add_u32_e32 v3, 1, v1
	s_nop 0
	v_cndmask_b32_e64 v2, v1, v2, s[6:7]
	v_fma_f32 v1, -v3, v1, v0
	v_cmp_lt_f32_e64 s[6:7], 0, v1
	s_nop 1
	v_cndmask_b32_e64 v1, v2, v3, s[6:7]
	v_mul_f32_e32 v2, 0x37800000, v1
	v_cndmask_b32_e32 v1, v1, v2, vcc
	v_cmp_class_f32_e32 vcc, v0, v175
	s_nop 1
	v_cndmask_b32_e32 v0, v1, v0, vcc
	v_div_scale_f32 v1, s[6:7], v0, v0, 1.0
	v_rcp_f32_e32 v2, v1
	s_nop 0
	v_fma_f32 v3, -v1, v2, 1.0
	v_fmac_f32_e32 v2, v3, v2
	v_div_scale_f32 v3, vcc, 1.0, v0, 1.0
	v_mul_f32_e32 v6, v3, v2
	v_fma_f32 v7, -v1, v6, v3
	v_fmac_f32_e32 v6, v7, v2
	v_fma_f32 v1, -v1, v6, v3
	v_div_fmas_f32 v1, v1, v2, v6
	v_div_fixup_f32 v6, v1, v0, 1.0
	v_or_b32_e32 v0, 24, v152
	v_mov_b32_e32 v1, v153
	v_lshl_add_u64 v[0:1], v[32:33], 0, v[0:1]
	v_lshlrev_b64 v[0:1], 11, v[0:1]
	v_or_b32_e32 v7, v0, v40
	v_or_b32_e32 v0, 0x600, v7
	v_lshl_add_u64 v[2:3], s[10:11], 0, v[0:1]
	s_nop 0
	v_mov_b32_e32 v3, v1
	v_lshl_add_u64 v[0:1], s[12:13], 0, v[0:1]
	v_lshlrev_b32_e32 v10, 16, v114
	v_or_b32_e32 v2, 0x640, v7
	v_lshl_add_u64 v[8:9], s[10:11], 0, v[2:3]
	s_nop 0
	v_mul_f32_e32 v8, 0xbfb8aa3b, v10
	v_exp_f32_e32 v8, v8
	v_lshlrev_b32_e32 v7, 16, v115
	v_add_f32_e32 v8, 1.0, v8
	v_div_scale_f32 v9, s[6:7], v8, v8, v10
	v_rcp_f32_e32 v11, v9
	s_nop 0
	v_fma_f32 v12, -v9, v11, 1.0
	v_fmac_f32_e32 v11, v12, v11
	v_div_scale_f32 v12, vcc, v10, v8, v10
	v_mul_f32_e32 v16, v12, v11
	v_fma_f32 v17, -v9, v16, v12
	v_fmac_f32_e32 v16, v17, v11
	v_fma_f32 v9, -v9, v16, v12
	v_div_fmas_f32 v9, v9, v11, v16
	v_div_fixup_f32 v8, v9, v8, v10
	v_mul_f32_e32 v9, 0xbfb8aa3b, v7
	v_exp_f32_e32 v9, v9
	v_mul_f32_e32 v5, v5, v8
	v_mul_f32_e32 v5, v6, v5
	v_mul_f32_e32 v5, v39, v5
	v_add_f32_e32 v9, 1.0, v9
	v_div_scale_f32 v10, s[6:7], v9, v9, v7
	v_rcp_f32_e32 v11, v10
	v_cvt_pk_bf16_f32 v5, v5, s0
	global_store_short v[0:1], v5, off
	v_fma_f32 v12, -v10, v11, 1.0
	v_fmac_f32_e32 v11, v12, v11
	v_div_scale_f32 v12, vcc, v7, v9, v7
	v_mul_f32_e32 v16, v12, v11
	v_fma_f32 v17, -v10, v16, v12
	v_fmac_f32_e32 v16, v17, v11
	v_fma_f32 v10, -v10, v16, v12
	v_div_fmas_f32 v10, v10, v11, v16
	v_div_fixup_f32 v7, v10, v9, v7
	v_mul_f32_e32 v0, v4, v7
	v_mul_f32_e32 v0, v6, v0
	v_mul_f32_e32 v0, v38, v0
	v_cvt_pk_bf16_f32 v4, v0, s0
	v_lshl_add_u64 v[0:1], s[12:13], 0, v[2:3]
	global_store_short v[0:1], v4, off
; __device__ __forceinline__ unsigned pk2(float lo, float hi) { return pg8::pk_bf16_rne(lo, hi); }
; __device__ __forceinline__ float bf2f(unsigned short u) { return __uint_as_float(((unsigned)u) << 16); }
; __device__ __forceinline__ float half_sum(float v) { v = row16_allsum(v); v = rows_pair_sum(v); return v; }
; __device__ __forceinline__ int crow(int r, int hi) { return (r & 3) + 8 * (r >> 2) + 4 * hi; }
; __device__ __forceinline__ void ret_out(const Params& P, int l, unsigned char* lds, int u, int tid) {
;     ...
;     for (int r = 0; r < 16; ++r) {
;         const float mean = half_sum(o0[r] + o1[r]) * (1.0f / 64.0f);
;         const float d0 = o0[r] - mean, d1 = o1[r] - mean;
;         const float var = half_sum(d0 * d0 + d1 * d1) * (1.0f / 64.0f);
;         const float rstd = 1.0f / sqrtf(var + 1e-5f);
;         const size_t t = tc + c0f + crow(r, hi);
;         const float ga = bf2f(ZR[t * 1024 + 768 + h * 64 + r32]), gb = bf2f(ZR[t * 1024 + 768 + h * 64 + 32 + r32]);
;         const float sa = ga / (1.0f + __expf(-ga)), sb = gb / (1.0f + __expf(-gb));
;         MIX[t * 1024 + 768 + h * 64 + r32] = (bf16_t)(pk2(sa * d0 * rstd * g0, 0.f) & 0xffffu);
;         MIX[t * 1024 + 768 + h * 64 + 32 + r32] = (bf16_t)(pk2(sb * d1 * rstd * g1, 0.f) & 0xffffu);
;     }
	v_add_f32_e32 v0, v13, v29
	s_nop 1
	v_add_f32_dpp v0, v0, v0 row_ror:8 row_mask:0xf bank_mask:0xf bound_ctrl:1
	s_nop 1
	v_add_f32_dpp v0, v0, v0 row_ror:4 row_mask:0xf bank_mask:0xf bound_ctrl:1
	s_nop 1
	v_add_f32_dpp v0, v0, v0 row_ror:2 row_mask:0xf bank_mask:0xf bound_ctrl:1
	s_nop 1
	v_add_f32_dpp v0, v0, v0 row_ror:1 row_mask:0xf bank_mask:0xf bound_ctrl:1
	v_mov_b32_e32 v1, v0
	s_nop 1
	v_permlane16_swap_b32_e32 v0, v1
	v_add_f32_e32 v0, v0, v1
	v_fmamk_f32 v4, v0, 0xbc800000, v29
	v_fmamk_f32 v5, v0, 0xbc800000, v13
	v_mul_f32_e32 v0, v4, v4
	v_fmac_f32_e32 v0, v5, v5
	s_nop 1
	v_add_f32_dpp v0, v0, v0 row_ror:8 row_mask:0xf bank_mask:0xf bound_ctrl:1
	s_nop 1
	v_add_f32_dpp v0, v0, v0 row_ror:4 row_mask:0xf bank_mask:0xf bound_ctrl:1
	s_nop 1
	v_add_f32_dpp v0, v0, v0 row_ror:2 row_mask:0xf bank_mask:0xf bound_ctrl:1
	s_nop 1
	v_add_f32_dpp v0, v0, v0 row_ror:1 row_mask:0xf bank_mask:0xf bound_ctrl:1
	v_mov_b32_e32 v1, v0
	s_nop 1
	v_permlane16_swap_b32_e32 v0, v1
	v_add_f32_e32 v0, v0, v1
	v_fmamk_f32 v0, v0, 0x3c800000, v200
	v_cmp_gt_f32_e32 vcc, s43, v0
	v_mul_f32_e32 v1, 0x4f800000, v0
	s_nop 0
	v_cndmask_b32_e32 v0, v0, v1, vcc
	v_sqrt_f32_e32 v1, v0
	s_nop 0
	v_add_u32_e32 v2, -1, v1
	v_fma_f32 v3, -v2, v1, v0
	v_cmp_ge_f32_e64 s[6:7], 0, v3
	v_add_u32_e32 v3, 1, v1
	s_nop 0
	v_cndmask_b32_e64 v2, v1, v2, s[6:7]
	v_fma_f32 v1, -v3, v1, v0
	v_cmp_lt_f32_e64 s[6:7], 0, v1
	s_nop 1
	v_cndmask_b32_e64 v1, v2, v3, s[6:7]
	v_mul_f32_e32 v2, 0x37800000, v1
	v_cndmask_b32_e32 v1, v1, v2, vcc
	v_cmp_class_f32_e32 vcc, v0, v175
	s_nop 1
	v_cndmask_b32_e32 v0, v1, v0, vcc
	v_div_scale_f32 v1, s[6:7], v0, v0, 1.0
	v_rcp_f32_e32 v2, v1
	s_nop 0
	v_fma_f32 v3, -v1, v2, 1.0
	v_fmac_f32_e32 v2, v3, v2
	v_div_scale_f32 v3, vcc, 1.0, v0, 1.0
	v_mul_f32_e32 v6, v3, v2
	v_fma_f32 v7, -v1, v6, v3
	v_fmac_f32_e32 v6, v7, v2
	v_fma_f32 v1, -v1, v6, v3
	v_div_fmas_f32 v1, v1, v2, v6
	v_div_fixup_f32 v6, v1, v0, 1.0
	v_or_b32_e32 v0, 25, v152
	v_mov_b32_e32 v1, v153
	v_lshl_add_u64 v[0:1], v[32:33], 0, v[0:1]
	v_lshlrev_b64 v[0:1], 11, v[0:1]
	v_or_b32_e32 v7, v0, v40
	v_or_b32_e32 v0, 0x600, v7
	v_lshl_add_u64 v[2:3], s[10:11], 0, v[0:1]
	s_nop 0
	v_mov_b32_e32 v3, v1
	v_lshl_add_u64 v[0:1], s[12:13], 0, v[0:1]
	v_lshlrev_b32_e32 v10, 16, v116
	v_or_b32_e32 v2, 0x640, v7
	v_lshl_add_u64 v[8:9], s[10:11], 0, v[2:3]
	s_nop 0
	v_mul_f32_e32 v8, 0xbfb8aa3b, v10
	v_exp_f32_e32 v8, v8
	v_lshlrev_b32_e32 v7, 16, v117
	v_add_f32_e32 v8, 1.0, v8
	v_div_scale_f32 v9, s[6:7], v8, v8, v10
	v_rcp_f32_e32 v11, v9
	s_nop 0
	v_fma_f32 v12, -v9, v11, 1.0
	v_fmac_f32_e32 v11, v12, v11
	v_div_scale_f32 v12, vcc, v10, v8, v10
	v_mul_f32_e32 v13, v12, v11
	v_fma_f32 v16, -v9, v13, v12
	v_fmac_f32_e32 v13, v16, v11
	v_fma_f32 v9, -v9, v13, v12
	v_div_fmas_f32 v9, v9, v11, v13
	v_div_fixup_f32 v8, v9, v8, v10
	v_mul_f32_e32 v9, 0xbfb8aa3b, v7
	v_exp_f32_e32 v9, v9
	v_mul_f32_e32 v5, v5, v8
	v_mul_f32_e32 v5, v6, v5
	v_mul_f32_e32 v5, v39, v5
	v_add_f32_e32 v9, 1.0, v9
	v_div_scale_f32 v10, s[6:7], v9, v9, v7
	v_rcp_f32_e32 v11, v10
	v_cvt_pk_bf16_f32 v5, v5, s0
	global_store_short v[0:1], v5, off
	v_fma_f32 v12, -v10, v11, 1.0
	v_fmac_f32_e32 v11, v12, v11
	v_div_scale_f32 v12, vcc, v7, v9, v7
	v_mul_f32_e32 v13, v12, v11
	v_fma_f32 v16, -v10, v13, v12
	v_fmac_f32_e32 v13, v16, v11
	v_fma_f32 v10, -v10, v13, v12
	v_div_fmas_f32 v10, v10, v11, v13
	v_div_fixup_f32 v7, v10, v9, v7
	v_mul_f32_e32 v0, v4, v7
	v_mul_f32_e32 v0, v6, v0
	v_mul_f32_e32 v0, v38, v0
	v_cvt_pk_bf16_f32 v4, v0, s0
	v_lshl_add_u64 v[0:1], s[12:13], 0, v[2:3]
	global_store_short v[0:1], v4, off
	v_add_f32_e32 v0, v14, v30
	s_nop 1
	v_add_f32_dpp v0, v0, v0 row_ror:8 row_mask:0xf bank_mask:0xf bound_ctrl:1
	s_nop 1
	v_add_f32_dpp v0, v0, v0 row_ror:4 row_mask:0xf bank_mask:0xf bound_ctrl:1
	s_nop 1
	v_add_f32_dpp v0, v0, v0 row_ror:2 row_mask:0xf bank_mask:0xf bound_ctrl:1
	s_nop 1
	v_add_f32_dpp v0, v0, v0 row_ror:1 row_mask:0xf bank_mask:0xf bound_ctrl:1
	v_mov_b32_e32 v1, v0
	s_nop 1
	v_permlane16_swap_b32_e32 v0, v1
	v_add_f32_e32 v0, v0, v1
	v_fmamk_f32 v4, v0, 0xbc800000, v30
	v_fmamk_f32 v5, v0, 0xbc800000, v14
	v_mul_f32_e32 v0, v4, v4
	v_fmac_f32_e32 v0, v5, v5
	s_nop 1
	v_add_f32_dpp v0, v0, v0 row_ror:8 row_mask:0xf bank_mask:0xf bound_ctrl:1
	s_nop 1
	v_add_f32_dpp v0, v0, v0 row_ror:4 row_mask:0xf bank_mask:0xf bound_ctrl:1
	s_nop 1
	v_add_f32_dpp v0, v0, v0 row_ror:2 row_mask:0xf bank_mask:0xf bound_ctrl:1
	s_nop 1
	v_add_f32_dpp v0, v0, v0 row_ror:1 row_mask:0xf bank_mask:0xf bound_ctrl:1
	v_mov_b32_e32 v1, v0
	s_nop 1
	v_permlane16_swap_b32_e32 v0, v1
	v_add_f32_e32 v0, v0, v1
	v_fmamk_f32 v0, v0, 0x3c800000, v200
	v_cmp_gt_f32_e32 vcc, s43, v0
	v_mul_f32_e32 v1, 0x4f800000, v0
	s_nop 0
	v_cndmask_b32_e32 v0, v0, v1, vcc
	v_sqrt_f32_e32 v1, v0
	s_nop 0
	v_add_u32_e32 v2, -1, v1
	v_fma_f32 v3, -v2, v1, v0
	v_cmp_ge_f32_e64 s[6:7], 0, v3
	v_add_u32_e32 v3, 1, v1
	s_nop 0
	v_cndmask_b32_e64 v2, v1, v2, s[6:7]
	v_fma_f32 v1, -v3, v1, v0
	v_cmp_lt_f32_e64 s[6:7], 0, v1
	s_nop 1
	v_cndmask_b32_e64 v1, v2, v3, s[6:7]
	v_mul_f32_e32 v2, 0x37800000, v1
	v_cndmask_b32_e32 v1, v1, v2, vcc
	v_cmp_class_f32_e32 vcc, v0, v175
	s_nop 1
	v_cndmask_b32_e32 v0, v1, v0, vcc
	v_div_scale_f32 v1, s[6:7], v0, v0, 1.0
	v_rcp_f32_e32 v2, v1
	s_nop 0
	v_fma_f32 v3, -v1, v2, 1.0
	v_fmac_f32_e32 v2, v3, v2
	v_div_scale_f32 v3, vcc, 1.0, v0, 1.0
; __device__ __forceinline__ unsigned pk2(float lo, float hi) { return pg8::pk_bf16_rne(lo, hi); }
; __device__ __forceinline__ float bf2f(unsigned short u) { return __uint_as_float(((unsigned)u) << 16); }
; __device__ __forceinline__ float half_sum(float v) { v = row16_allsum(v); v = rows_pair_sum(v); return v; }
; __device__ __forceinline__ int crow(int r, int hi) { return (r & 3) + 8 * (r >> 2) + 4 * hi; }
; __device__ __forceinline__ void ret_out(const Params& P, int l, unsigned char* lds, int u, int tid) {
;     ...
;     for (int r = 0; r < 16; ++r) {
;         const float mean = half_sum(o0[r] + o1[r]) * (1.0f / 64.0f);
;         const float d0 = o0[r] - mean, d1 = o1[r] - mean;
;         const float var = half_sum(d0 * d0 + d1 * d1) * (1.0f / 64.0f);
;         const float rstd = 1.0f / sqrtf(var + 1e-5f);
;         const size_t t = tc + c0f + crow(r, hi);
;         const float ga = bf2f(ZR[t * 1024 + 768 + h * 64 + r32]), gb = bf2f(ZR[t * 1024 + 768 + h * 64 + 32 + r32]);
;         const float sa = ga / (1.0f + __expf(-ga)), sb = gb / (1.0f + __expf(-gb));
;         MIX[t * 1024 + 768 + h * 64 + r32] = (bf16_t)(pk2(sa * d0 * rstd * g0, 0.f) & 0xffffu);
;         MIX[t * 1024 + 768 + h * 64 + 32 + r32] = (bf16_t)(pk2(sb * d1 * rstd * g1, 0.f) & 0xffffu);
;     }
;     __syncthreads();
	v_mul_f32_e32 v6, v3, v2
	v_fma_f32 v7, -v1, v6, v3
	v_fmac_f32_e32 v6, v7, v2
	v_fma_f32 v1, -v1, v6, v3
	v_div_fmas_f32 v1, v1, v2, v6
	v_div_fixup_f32 v6, v1, v0, 1.0
	v_or_b32_e32 v0, 26, v152
	v_mov_b32_e32 v1, v153
	v_lshl_add_u64 v[0:1], v[32:33], 0, v[0:1]
	v_lshlrev_b64 v[0:1], 11, v[0:1]
	v_or_b32_e32 v7, v0, v40
	v_or_b32_e32 v0, 0x600, v7
	v_lshl_add_u64 v[2:3], s[10:11], 0, v[0:1]
	s_nop 0
	v_mov_b32_e32 v3, v1
	v_lshl_add_u64 v[0:1], s[12:13], 0, v[0:1]
	v_or_b32_e32 v152, 27, v152
	v_lshlrev_b32_e32 v10, 16, v118
	v_or_b32_e32 v2, 0x640, v7
	v_lshl_add_u64 v[8:9], s[10:11], 0, v[2:3]
	s_nop 0
	v_mul_f32_e32 v8, 0xbfb8aa3b, v10
	v_exp_f32_e32 v8, v8
	v_lshlrev_b32_e32 v7, 16, v119
	v_add_f32_e32 v8, 1.0, v8
	v_div_scale_f32 v9, s[6:7], v8, v8, v10
	v_rcp_f32_e32 v11, v9
	s_nop 0
	v_fma_f32 v12, -v9, v11, 1.0
	v_fmac_f32_e32 v11, v12, v11
	v_div_scale_f32 v12, vcc, v10, v8, v10
	v_mul_f32_e32 v13, v12, v11
	v_fma_f32 v14, -v9, v13, v12
	v_fmac_f32_e32 v13, v14, v11
	v_fma_f32 v9, -v9, v13, v12
	v_div_fmas_f32 v9, v9, v11, v13
	v_div_fixup_f32 v8, v9, v8, v10
	v_mul_f32_e32 v9, 0xbfb8aa3b, v7
	v_exp_f32_e32 v9, v9
	v_mul_f32_e32 v5, v5, v8
	v_mul_f32_e32 v5, v6, v5
	v_mul_f32_e32 v5, v39, v5
	v_add_f32_e32 v9, 1.0, v9
	v_div_scale_f32 v10, s[6:7], v9, v9, v7
	v_rcp_f32_e32 v11, v10
	v_cvt_pk_bf16_f32 v5, v5, s0
	global_store_short v[0:1], v5, off
	v_fma_f32 v12, -v10, v11, 1.0
	v_fmac_f32_e32 v11, v12, v11
	v_div_scale_f32 v12, vcc, v7, v9, v7
	v_mul_f32_e32 v13, v12, v11
	v_fma_f32 v14, -v10, v13, v12
	v_fmac_f32_e32 v13, v14, v11
	v_fma_f32 v10, -v10, v13, v12
	v_div_fmas_f32 v10, v10, v11, v13
	v_div_fixup_f32 v7, v10, v9, v7
	v_mul_f32_e32 v0, v4, v7
	v_mul_f32_e32 v0, v6, v0
	v_mul_f32_e32 v0, v38, v0
	v_cvt_pk_bf16_f32 v4, v0, s0
	v_lshl_add_u64 v[0:1], s[12:13], 0, v[2:3]
	global_store_short v[0:1], v4, off
	v_add_f32_e32 v0, v15, v31
	s_nop 1
	v_add_f32_dpp v0, v0, v0 row_ror:8 row_mask:0xf bank_mask:0xf bound_ctrl:1
	s_nop 1
	v_add_f32_dpp v0, v0, v0 row_ror:4 row_mask:0xf bank_mask:0xf bound_ctrl:1
	s_nop 1
	v_add_f32_dpp v0, v0, v0 row_ror:2 row_mask:0xf bank_mask:0xf bound_ctrl:1
	s_nop 1
	v_add_f32_dpp v0, v0, v0 row_ror:1 row_mask:0xf bank_mask:0xf bound_ctrl:1
	v_mov_b32_e32 v1, v0
	s_nop 1
	v_permlane16_swap_b32_e32 v0, v1
	v_add_f32_e32 v0, v0, v1
	v_fmac_f32_e32 v31, 0xbc800000, v0
	v_fmac_f32_e32 v15, 0xbc800000, v0
	v_mul_f32_e32 v0, v31, v31
	v_fmac_f32_e32 v0, v15, v15
	s_nop 1
	v_add_f32_dpp v0, v0, v0 row_ror:8 row_mask:0xf bank_mask:0xf bound_ctrl:1
	s_nop 1
	v_add_f32_dpp v0, v0, v0 row_ror:4 row_mask:0xf bank_mask:0xf bound_ctrl:1
	s_nop 1
	v_add_f32_dpp v0, v0, v0 row_ror:2 row_mask:0xf bank_mask:0xf bound_ctrl:1
	s_nop 1
	v_add_f32_dpp v0, v0, v0 row_ror:1 row_mask:0xf bank_mask:0xf bound_ctrl:1
	v_mov_b32_e32 v1, v0
	s_nop 1
	v_permlane16_swap_b32_e32 v0, v1
	v_add_f32_e32 v0, v0, v1
	v_fmamk_f32 v0, v0, 0x3c800000, v200
	v_cmp_gt_f32_e32 vcc, s43, v0
	v_mul_f32_e32 v1, 0x4f800000, v0
	s_nop 0
	v_cndmask_b32_e32 v0, v0, v1, vcc
	v_sqrt_f32_e32 v1, v0
	s_nop 0
	v_add_u32_e32 v2, -1, v1
	v_fma_f32 v3, -v2, v1, v0
	v_cmp_ge_f32_e64 s[6:7], 0, v3
	v_add_u32_e32 v3, 1, v1
	s_nop 0
	v_cndmask_b32_e64 v2, v1, v2, s[6:7]
	v_fma_f32 v1, -v3, v1, v0
	v_cmp_lt_f32_e64 s[6:7], 0, v1
	s_nop 1
	v_cndmask_b32_e64 v1, v2, v3, s[6:7]
	v_mul_f32_e32 v2, 0x37800000, v1
	v_cndmask_b32_e32 v1, v1, v2, vcc
	v_cmp_class_f32_e32 vcc, v0, v175
	s_nop 1
	v_cndmask_b32_e32 v0, v1, v0, vcc
	v_div_scale_f32 v1, s[6:7], v0, v0, 1.0
	v_rcp_f32_e32 v2, v1
	s_nop 0
	v_fma_f32 v3, -v1, v2, 1.0
	v_fmac_f32_e32 v2, v3, v2
	v_div_scale_f32 v3, vcc, 1.0, v0, 1.0
	v_mul_f32_e32 v4, v3, v2
	v_fma_f32 v5, -v1, v4, v3
	v_fmac_f32_e32 v4, v5, v2
	v_fma_f32 v1, -v1, v4, v3
	v_div_fmas_f32 v1, v1, v2, v4
	v_div_fixup_f32 v4, v1, v0, 1.0
	v_lshl_add_u64 v[0:1], v[32:33], 0, v[152:153]
	v_lshlrev_b64 v[0:1], 11, v[0:1]
	v_or_b32_e32 v5, v0, v40
	v_or_b32_e32 v0, 0x600, v5
	v_lshl_add_u64 v[2:3], s[10:11], 0, v[0:1]
	s_nop 0
	v_mov_b32_e32 v3, v1
	v_lshl_add_u64 v[0:1], s[12:13], 0, v[0:1]
	v_lshlrev_b32_e32 v8, 16, v120
	v_or_b32_e32 v2, 0x640, v5
	v_lshl_add_u64 v[6:7], s[10:11], 0, v[2:3]
	s_nop 0
	v_mul_f32_e32 v6, 0xbfb8aa3b, v8
	v_exp_f32_e32 v6, v6
	v_lshlrev_b32_e32 v5, 16, v121
	v_add_f32_e32 v6, 1.0, v6
	v_div_scale_f32 v7, s[6:7], v6, v6, v8
	v_rcp_f32_e32 v9, v7
	s_nop 0
	v_fma_f32 v10, -v7, v9, 1.0
	v_fmac_f32_e32 v9, v10, v9
	v_div_scale_f32 v10, vcc, v8, v6, v8
	v_mul_f32_e32 v11, v10, v9
	v_fma_f32 v12, -v7, v11, v10
	v_fmac_f32_e32 v11, v12, v9
	v_fma_f32 v7, -v7, v11, v10
	v_div_fmas_f32 v7, v7, v9, v11
	v_div_fixup_f32 v6, v7, v6, v8
	v_mul_f32_e32 v7, 0xbfb8aa3b, v5
	v_exp_f32_e32 v7, v7
	v_mul_f32_e32 v6, v15, v6
	v_mul_f32_e32 v6, v4, v6
	v_mul_f32_e32 v6, v39, v6
	v_add_f32_e32 v7, 1.0, v7
	v_div_scale_f32 v8, s[6:7], v7, v7, v5
	v_rcp_f32_e32 v9, v8
	v_cvt_pk_bf16_f32 v6, v6, s0
	global_store_short v[0:1], v6, off
	v_fma_f32 v10, -v8, v9, 1.0
	v_fmac_f32_e32 v9, v10, v9
	v_div_scale_f32 v10, vcc, v5, v7, v5
	v_mul_f32_e32 v11, v10, v9
	v_fma_f32 v12, -v8, v11, v10
	v_fmac_f32_e32 v11, v12, v9
	v_fma_f32 v8, -v8, v11, v10
	v_div_fmas_f32 v8, v8, v9, v11
	v_div_fixup_f32 v5, v8, v7, v5
	v_mul_f32_e32 v0, v31, v5
	v_mul_f32_e32 v0, v4, v0
	v_mul_f32_e32 v0, v38, v0
	v_cvt_pk_bf16_f32 v4, v0, s0
	v_lshl_add_u64 v[0:1], s[12:13], 0, v[2:3]
	global_store_short v[0:1], v4, off
	s_barrier
